# y-phase: ACST/BST rows staged in LDS, 5-deep LDS read ring for state MFMAs, epilogue Z loads batched
# speedup vs baseline: 1.0507x; 1.0507x over previous
.LBB0_2098:
	s_or_b64 exec, exec, s[0:1]
	s_mov_b64 s[4:5], s[60:61]
	s_mov_b64 s[0:1], s[60:61]
	s_mov_b64 s[2:3], s[60:61]
	v_mov_b32_e32 v15, v218
	s_waitcnt lgkmcnt(0)
	v_mov_b32_e32 v0, v219
	s_barrier
	s_nop 0
	v_readfirstlane_b32 s13, v0
	s_cmpk_gt_i32 s13, 0x3ff
	s_cbranch_scc1 .LBB0_2114
	s_load_dwordx2 s[4:5], s[4:5], 0xe8
	s_nop 0
	s_load_dwordx2 s[0:1], s[0:1], 0xe8
	s_nop 0
	s_load_dwordx2 s[2:3], s[2:3], 0x78
	v_ashrrev_i32_e32 v16, 6, v15
	v_bfe_u32 v3, v15, 5, 1
	v_lshlrev_b32_e32 v0, 4, v15
	s_waitcnt lgkmcnt(0)
	s_add_u32 s33, s4, 0x508000
	s_addc_u32 s18, s5, 0
	s_and_b64 s[4:5], s[8:9], exec
	s_cselect_b32 s4, 0x80, 0
	s_add_u32 s2, s2, s4
	v_and_b32_e32 v173, 31, v15
	v_lshlrev_b32_e32 v168, 5, v16
	v_and_b32_e32 v0, 0xf0, v0
	v_lshlrev_b32_e32 v4, 4, v3
	v_mov_b32_e32 v5, v129
	v_writelane_b32 v252, s2, 51
	s_addc_u32 s2, s3, 0
	v_or_b32_e32 v170, v168, v173
	v_add_u32_e32 v1, v220, v0
	v_lshlrev_b32_e32 v0, 2, v3
	v_lshl_add_u64 v[6:7], s[0:1], 0, v[4:5]
	s_mov_b64 s[0:1], 0x908000
	v_writelane_b32 v252, s2, 52
	v_lshl_add_u64 v[174:175], v[6:7], 0, s[0:1]
	v_cmp_le_i32_e64 s[0:1], v0, v170
	v_or_b32_e32 v17, 1, v0
	v_cmp_lt_i32_e64 s[4:5], -1, v16
	v_writelane_b32 v252, s0, 53
	v_cmp_gt_i32_e64 s[6:7], 1, v16
	v_cmp_lt_i32_e64 s[74:75], 0, v16
	v_writelane_b32 v252, s1, 54
	v_cmp_ge_i32_e64 s[0:1], v0, v170
	v_cmp_gt_i32_e64 s[76:77], 2, v16
	v_cmp_lt_i32_e64 s[50:51], 1, v16
	v_writelane_b32 v252, s0, 55
	v_cmp_gt_i32_e64 s[52:53], 3, v16
	v_cmp_lt_i32_e64 s[28:29], 2, v16
	v_writelane_b32 v252, s1, 56
	v_cmp_lt_i32_e64 s[0:1], v0, v170
	v_cmp_gt_i32_e64 s[30:31], 4, v16
	v_or_b32_e32 v16, 0x60, v0
	v_writelane_b32 v252, s0, 57
	v_cmp_le_i32_e64 s[34:35], v16, v170
	v_cmp_ge_i32_e64 s[36:37], v16, v170
	v_writelane_b32 v252, s1, 58
	v_cmp_ge_i32_e64 s[0:1], v17, v170
	v_or_b32_e32 v17, 2, v0
	v_or_b32_e32 v16, 0x61, v0
	v_writelane_b32 v252, s0, 59
	v_cmp_le_i32_e64 s[38:39], v16, v170
	v_cmp_ge_i32_e64 s[40:41], v16, v170
	v_writelane_b32 v252, s1, 60
	v_cmp_le_i32_e64 s[0:1], v17, v170
	v_or_b32_e32 v16, 0x62, v0
	v_cmp_le_i32_e64 s[42:43], v16, v170
	v_writelane_b32 v252, s0, 61
	v_cmp_ge_i32_e64 s[44:45], v16, v170
	v_or_b32_e32 v16, 0x63, v0
	v_writelane_b32 v252, s1, 62
	v_cmp_ge_i32_e64 s[0:1], v17, v170
	v_or_b32_e32 v17, 3, v0
	v_lshlrev_b32_e32 v2, 3, v15
	v_writelane_b32 v252, s0, 63
	v_lshrrev_b32_e32 v12, 4, v15
	v_add_u32_e32 v13, 0x100, v15
	v_writelane_b32 v253, s1, 0
	v_cmp_le_i32_e64 s[0:1], v17, v170
	v_add_u32_e32 v14, 0x200, v15
	v_add_u32_e32 v15, 0x300, v15
	v_writelane_b32 v253, s0, 1
	v_cmp_le_i32_e64 s[46:47], v16, v170
	v_cmp_ge_i32_e64 s[48:49], v16, v170
	v_writelane_b32 v253, s1, 2
	v_cmp_ge_i32_e64 s[0:1], v17, v170
	v_or_b32_e32 v17, 8, v0
	v_or_b32_e32 v16, 0x68, v0
	v_writelane_b32 v253, s0, 3
	v_lshrrev_b32_e32 v13, 4, v13
	v_lshrrev_b32_e32 v14, 4, v14
	v_writelane_b32 v253, s1, 4
	v_cmp_le_i32_e64 s[0:1], v17, v170
	v_lshrrev_b32_e32 v15, 4, v15
	v_cmp_le_i32_e64 s[54:55], v16, v170
	v_writelane_b32 v253, s0, 5
	v_cmp_ge_i32_e64 s[56:57], v16, v170
	v_or_b32_e32 v16, 0x69, v0
	v_writelane_b32 v253, s1, 6
	v_cmp_ge_i32_e64 s[0:1], v17, v170
	v_or_b32_e32 v17, 9, v0
	v_mad_u32_u24 v198, v173, s59, v220
	v_writelane_b32 v253, s0, 7
	v_mul_lo_u32 v12, v12, s59
	v_mul_lo_u32 v13, v13, s59
	v_writelane_b32 v253, s1, 8
	v_cmp_le_i32_e64 s[0:1], v17, v170
	v_mul_lo_u32 v14, v14, s59
	v_mul_lo_u32 v15, v15, s59
	v_writelane_b32 v253, s0, 9
	v_cmp_le_i32_e64 s[58:59], v16, v170
	v_cmp_ge_i32_e64 s[60:61], v16, v170
	v_writelane_b32 v253, s1, 10
	v_cmp_ge_i32_e64 s[0:1], v17, v170
	v_or_b32_e32 v17, 10, v0
	v_or_b32_e32 v16, 0x6a, v0
	v_writelane_b32 v253, s0, 11
	v_cmp_le_i32_e64 s[62:63], v16, v170
	v_cmp_ge_i32_e64 s[64:65], v16, v170
	v_writelane_b32 v253, s1, 12
	v_cmp_le_i32_e64 s[0:1], v17, v170
	v_or_b32_e32 v16, 0x6b, v0
	v_cmp_le_i32_e64 s[66:67], v16, v170
	v_writelane_b32 v253, s0, 13
	v_cmp_ge_i32_e64 s[68:69], v16, v170
	v_or_b32_e32 v16, 0x70, v0
	v_writelane_b32 v253, s1, 14
	v_cmp_ge_i32_e64 s[0:1], v17, v170
	v_or_b32_e32 v17, 11, v0
	v_cmp_le_i32_e64 s[70:71], v16, v170
	v_writelane_b32 v253, s0, 15
	v_cmp_ge_i32_e64 s[72:73], v16, v170
	v_or_b32_e32 v16, 0x71, v0
	v_writelane_b32 v253, s1, 16
	v_cmp_le_i32_e64 s[0:1], v17, v170
	v_cmp_le_i32_e64 s[78:79], v16, v170
	v_cmp_ge_i32_e64 s[80:81], v16, v170
	v_writelane_b32 v253, s0, 17
	v_or_b32_e32 v16, 0x72, v0
	v_cmp_le_i32_e64 s[82:83], v16, v170
	v_writelane_b32 v253, s1, 18
	v_cmp_ge_i32_e64 s[0:1], v17, v170
	v_or_b32_e32 v17, 16, v0
	v_cmp_ge_i32_e64 s[84:85], v16, v170
	v_writelane_b32 v253, s0, 19
	v_or_b32_e32 v16, 0x73, v0
	v_cmp_le_i32_e64 s[86:87], v16, v170
	v_writelane_b32 v253, s1, 20
	v_cmp_le_i32_e64 s[0:1], v17, v170
	v_cmp_ge_i32_e64 s[88:89], v16, v170
	v_or_b32_e32 v16, 0x78, v0
	v_writelane_b32 v253, s0, 21
	v_cmp_le_i32_e64 s[90:91], v16, v170
	v_cmp_ge_i32_e64 s[92:93], v16, v170
	v_writelane_b32 v253, s1, 22
	v_cmp_ge_i32_e64 s[0:1], v17, v170
	v_or_b32_e32 v17, 17, v0
	v_or_b32_e32 v16, 0x79, v0
	v_writelane_b32 v253, s0, 23
	v_add_u32_e32 v199, v198, v4
	v_or_b32_e32 v200, v0, v168
	v_writelane_b32 v253, s1, 24
	v_cmp_le_i32_e64 s[0:1], v17, v170
	v_add_u32_e32 v4, 0x800, v2
	v_add_u32_e32 v6, 0x1000, v2
	v_writelane_b32 v253, s0, 25
	v_add_u32_e32 v8, 0x1800, v2
	v_cmp_le_i32_e64 s[94:95], v16, v170
	v_writelane_b32 v253, s1, 26
	v_cmp_ge_i32_e64 s[0:1], v17, v170
	v_or_b32_e32 v17, 18, v0
	v_cmp_ge_i32_e64 s[96:97], v16, v170
	v_writelane_b32 v253, s0, 27
	v_or_b32_e32 v16, 0x7a, v0
	v_lshlrev_b32_e32 v172, 3, v3
	v_writelane_b32 v253, s1, 28
	v_cmp_le_i32_e64 s[0:1], v17, v170
	v_mul_u32_u24_e32 v10, 0x110, v173
	v_lshl_add_u32 v11, v200, 1, v220
	v_writelane_b32 v253, s0, 29
	v_ashrrev_i32_e32 v3, 31, v2
	v_ashrrev_i32_e32 v5, 31, v4
	v_writelane_b32 v253, s1, 30
	v_cmp_ge_i32_e64 s[0:1], v17, v170
	v_or_b32_e32 v17, 19, v0
	v_ashrrev_i32_e32 v7, 31, v6
	v_writelane_b32 v253, s0, 31
	v_ashrrev_i32_e32 v9, 31, v8
	v_cmp_le_i32_e64 s[2:3], v16, v170
	v_writelane_b32 v253, s1, 32
	v_cmp_le_i32_e64 s[0:1], v17, v170
	v_cmp_ge_i32_e64 s[8:9], v16, v170
	v_or_b32_e32 v16, 0x7b, v0
	v_writelane_b32 v253, s0, 33
	v_ashrrev_i32_e32 v171, 31, v170
	v_ashrrev_i32_e32 v169, 31, v168
	v_writelane_b32 v253, s1, 34
	v_cmp_ge_i32_e64 s[0:1], v17, v170
	v_or_b32_e32 v17, 24, v0
	v_cmp_ge_i32_e64 s[10:11], v16, v170
	v_writelane_b32 v253, s0, 35
	v_lshlrev_b64 v[176:177], 1, v[2:3]
	v_lshlrev_b64 v[178:179], 1, v[4:5]
	v_writelane_b32 v253, s1, 36
	v_cmp_le_i32_e64 s[0:1], v17, v170
	v_lshlrev_b64 v[180:181], 1, v[6:7]
	v_lshlrev_b64 v[182:183], 1, v[8:9]
	v_writelane_b32 v253, s0, 37
	v_add_u32_e32 v201, v1, v12
	v_add_u32_e32 v202, v1, v13
	v_writelane_b32 v253, s1, 38
	v_cmp_ge_i32_e64 s[0:1], v17, v170
	v_or_b32_e32 v17, 25, v0
	v_add_u32_e32 v203, v1, v14
	v_writelane_b32 v253, s0, 39
	v_add_u32_e32 v204, v1, v15
	v_lshlrev_b32_e32 v128, 2, v0
	v_writelane_b32 v253, s1, 40
	v_cmp_le_i32_e64 s[0:1], v17, v170
	v_add_u32_e32 v205, v11, v10
	s_nop 0
	v_writelane_b32 v253, s0, 41
	s_nop 1
	v_writelane_b32 v253, s1, 42
	v_cmp_ge_i32_e64 s[0:1], v17, v170
	v_or_b32_e32 v17, 26, v0
	s_nop 0
	v_writelane_b32 v253, s0, 43
	s_nop 1
	v_writelane_b32 v253, s1, 44
	v_cmp_le_i32_e64 s[0:1], v17, v170
	s_nop 1
	v_writelane_b32 v253, s0, 45
	s_nop 1
	v_writelane_b32 v253, s1, 46
	v_cmp_ge_i32_e64 s[0:1], v17, v170
	v_or_b32_e32 v17, 27, v0
	s_nop 0
	v_writelane_b32 v253, s0, 47
	s_nop 1
	v_writelane_b32 v253, s1, 48
	v_cmp_le_i32_e64 s[0:1], v17, v170
	s_nop 1
	v_writelane_b32 v253, s0, 49
	s_nop 1
	v_writelane_b32 v253, s1, 50
	v_cmp_ge_i32_e64 s[0:1], v17, v170
	v_or_b32_e32 v17, 32, v0
	s_nop 0
	v_writelane_b32 v253, s0, 51
	s_nop 1
	v_writelane_b32 v253, s1, 52
	v_cmp_le_i32_e64 s[0:1], v17, v170
	s_nop 1
	v_writelane_b32 v253, s0, 53
	s_nop 1
	v_writelane_b32 v253, s1, 54
	v_cmp_ge_i32_e64 s[0:1], v17, v170
	v_or_b32_e32 v17, 33, v0
	s_nop 0
	v_writelane_b32 v253, s0, 55
	s_nop 1
	v_writelane_b32 v253, s1, 56
	v_cmp_le_i32_e64 s[0:1], v17, v170
	s_nop 1
	v_writelane_b32 v253, s0, 57
	s_nop 1
	v_writelane_b32 v253, s1, 58
	v_cmp_ge_i32_e64 s[0:1], v17, v170
	v_or_b32_e32 v17, 34, v0
	s_nop 0
	v_writelane_b32 v253, s0, 59
	s_nop 1
	v_writelane_b32 v253, s1, 60
	v_cmp_le_i32_e64 s[0:1], v17, v170
	s_nop 1
	v_writelane_b32 v253, s0, 61
	s_nop 1
	v_writelane_b32 v253, s1, 62
	v_cmp_ge_i32_e64 s[0:1], v17, v170
	v_or_b32_e32 v17, 35, v0
	s_nop 0
	v_writelane_b32 v253, s0, 63
	s_nop 1
	v_writelane_b32 v254, s1, 0
	v_cmp_le_i32_e64 s[0:1], v17, v170
	s_nop 1
	v_writelane_b32 v254, s0, 1
	s_nop 1
	v_writelane_b32 v254, s1, 2
	v_cmp_ge_i32_e64 s[0:1], v17, v170
	v_or_b32_e32 v17, 40, v0
	s_nop 0
	v_writelane_b32 v254, s0, 3
	s_nop 1
	v_writelane_b32 v254, s1, 4
	v_cmp_le_i32_e64 s[0:1], v17, v170
	s_nop 1
	v_writelane_b32 v254, s0, 5
	s_nop 1
	v_writelane_b32 v254, s1, 6
	v_cmp_ge_i32_e64 s[0:1], v17, v170
	v_or_b32_e32 v17, 41, v0
	s_nop 0
	v_writelane_b32 v254, s0, 7
	s_nop 1
	v_writelane_b32 v254, s1, 8
	v_cmp_le_i32_e64 s[0:1], v17, v170
	s_nop 1
	v_writelane_b32 v254, s0, 9
	s_nop 1
	v_writelane_b32 v254, s1, 10
	v_cmp_ge_i32_e64 s[0:1], v17, v170
	v_or_b32_e32 v17, 42, v0
	s_nop 0
	v_writelane_b32 v254, s0, 11
	s_nop 1
	v_writelane_b32 v254, s1, 12
	v_cmp_le_i32_e64 s[0:1], v17, v170
	s_nop 1
	v_writelane_b32 v254, s0, 13
	s_nop 1
	v_writelane_b32 v254, s1, 14
	v_cmp_ge_i32_e64 s[0:1], v17, v170
	v_or_b32_e32 v17, 43, v0
	s_nop 0
	v_writelane_b32 v254, s0, 15
	s_nop 1
	v_writelane_b32 v254, s1, 16
	v_cmp_le_i32_e64 s[0:1], v17, v170
	s_nop 1
	v_writelane_b32 v254, s0, 17
	s_nop 1
	v_writelane_b32 v254, s1, 18
	v_cmp_ge_i32_e64 s[0:1], v17, v170
	v_or_b32_e32 v17, 48, v0
	s_nop 0
	v_writelane_b32 v254, s0, 19
	s_nop 1
	v_writelane_b32 v254, s1, 20
	v_cmp_le_i32_e64 s[0:1], v17, v170
	s_nop 1
	v_writelane_b32 v254, s0, 21
	s_nop 1
	v_writelane_b32 v254, s1, 22
	v_cmp_ge_i32_e64 s[0:1], v17, v170
	v_or_b32_e32 v17, 49, v0
	s_nop 0
	v_writelane_b32 v254, s0, 23
	s_nop 1
	v_writelane_b32 v254, s1, 24
	v_cmp_le_i32_e64 s[0:1], v17, v170
	s_nop 1
	v_writelane_b32 v254, s0, 25
	s_nop 1
	v_writelane_b32 v254, s1, 26
	v_cmp_ge_i32_e64 s[0:1], v17, v170
	v_or_b32_e32 v17, 50, v0
	s_nop 0
	v_writelane_b32 v254, s0, 27
	s_nop 1
	v_writelane_b32 v254, s1, 28
	v_cmp_le_i32_e64 s[0:1], v17, v170
	s_nop 1
	v_writelane_b32 v254, s0, 29
	s_nop 1
	v_writelane_b32 v254, s1, 30
	v_cmp_ge_i32_e64 s[0:1], v17, v170
	v_or_b32_e32 v17, 51, v0
	s_nop 0
	v_writelane_b32 v254, s0, 31
	s_nop 1
	v_writelane_b32 v254, s1, 32
	v_cmp_le_i32_e64 s[0:1], v17, v170
	s_nop 1
	v_writelane_b32 v254, s0, 33
	s_nop 1
	v_writelane_b32 v254, s1, 34
	v_cmp_ge_i32_e64 s[0:1], v17, v170
	v_or_b32_e32 v17, 56, v0
	s_nop 0
	v_writelane_b32 v254, s0, 35
	s_nop 1
	v_writelane_b32 v254, s1, 36
	v_cmp_le_i32_e64 s[0:1], v17, v170
	s_nop 1
	v_writelane_b32 v254, s0, 37
	s_nop 1
	v_writelane_b32 v254, s1, 38
	v_cmp_ge_i32_e64 s[0:1], v17, v170
	v_or_b32_e32 v17, 57, v0
	s_nop 0
	v_writelane_b32 v254, s0, 39
	s_nop 1
	v_writelane_b32 v254, s1, 40
	v_cmp_le_i32_e64 s[0:1], v17, v170
	s_nop 1
	v_writelane_b32 v254, s0, 41
	s_nop 1
	v_writelane_b32 v254, s1, 42
	v_cmp_ge_i32_e64 s[0:1], v17, v170
	v_or_b32_e32 v17, 58, v0
	s_nop 0
	v_writelane_b32 v254, s0, 43
	s_nop 1
	v_writelane_b32 v254, s1, 44
	v_cmp_le_i32_e64 s[0:1], v17, v170
	s_nop 1
	v_writelane_b32 v254, s0, 45
	s_nop 1
	v_writelane_b32 v254, s1, 46
	v_cmp_ge_i32_e64 s[0:1], v17, v170
	v_or_b32_e32 v17, 59, v0
	s_nop 0
	v_writelane_b32 v254, s0, 47
	s_nop 1
	v_writelane_b32 v254, s1, 48
	v_cmp_le_i32_e64 s[0:1], v17, v170
	s_nop 1
	v_writelane_b32 v254, s0, 49
	s_nop 1
	v_writelane_b32 v254, s1, 50
	v_cmp_ge_i32_e64 s[0:1], v17, v170
	v_or_b32_e32 v17, 64, v0
	s_nop 0
	v_writelane_b32 v254, s0, 51
	s_nop 1
	v_writelane_b32 v254, s1, 52
	v_cmp_le_i32_e64 s[0:1], v17, v170
	s_nop 1
	v_writelane_b32 v254, s0, 53
	s_nop 1
	v_writelane_b32 v254, s1, 54
	v_cmp_ge_i32_e64 s[0:1], v17, v170
	v_or_b32_e32 v17, 0x41, v0
	s_nop 0
	v_writelane_b32 v254, s0, 55
	s_nop 1
	v_writelane_b32 v254, s1, 56
	v_cmp_le_i32_e64 s[0:1], v17, v170
	s_nop 1
	v_writelane_b32 v254, s0, 57
	s_nop 1
	v_writelane_b32 v254, s1, 58
	v_cmp_ge_i32_e64 s[0:1], v17, v170
	v_or_b32_e32 v17, 0x42, v0
	s_nop 0
	v_writelane_b32 v254, s0, 59
	s_nop 1
	v_writelane_b32 v254, s1, 60
	v_cmp_le_i32_e64 s[0:1], v17, v170
	s_nop 1
	v_writelane_b32 v254, s0, 61
	s_nop 1
	v_writelane_b32 v254, s1, 62
	v_cmp_ge_i32_e64 s[0:1], v17, v170
	v_or_b32_e32 v17, 0x43, v0
	s_nop 0
	v_writelane_b32 v254, s0, 63
	s_nop 1
	v_writelane_b32 v255, s1, 0
	v_cmp_le_i32_e64 s[0:1], v17, v170
	s_nop 1
	v_writelane_b32 v255, s0, 1
	s_nop 1
	v_writelane_b32 v255, s1, 2
	v_cmp_ge_i32_e64 s[0:1], v17, v170
	v_or_b32_e32 v17, 0x48, v0
	s_nop 0
	v_writelane_b32 v255, s0, 3
	s_nop 1
	v_writelane_b32 v255, s1, 4
	v_cmp_le_i32_e64 s[0:1], v17, v170
	s_nop 1
	v_writelane_b32 v255, s0, 5
	s_nop 1
	v_writelane_b32 v255, s1, 6
	v_cmp_ge_i32_e64 s[0:1], v17, v170
	v_or_b32_e32 v17, 0x49, v0
	s_nop 0
	v_writelane_b32 v255, s0, 7
	s_nop 1
	v_writelane_b32 v255, s1, 8
	v_cmp_le_i32_e64 s[0:1], v17, v170
	s_nop 1
	v_writelane_b32 v255, s0, 9
	s_nop 1
	v_writelane_b32 v255, s1, 10
	v_cmp_ge_i32_e64 s[0:1], v17, v170
	v_or_b32_e32 v17, 0x4a, v0
	s_nop 0
	v_writelane_b32 v255, s0, 11
	s_nop 1
	v_writelane_b32 v255, s1, 12
	v_cmp_le_i32_e64 s[0:1], v17, v170
	s_nop 1
	v_writelane_b32 v255, s0, 13
	s_nop 1
	v_writelane_b32 v255, s1, 14
	v_cmp_ge_i32_e64 s[0:1], v17, v170
	v_or_b32_e32 v17, 0x4b, v0
	s_nop 0
	v_writelane_b32 v255, s0, 15
	s_nop 1
	v_writelane_b32 v255, s1, 16
	v_cmp_le_i32_e64 s[0:1], v17, v170
	s_nop 1
	v_writelane_b32 v255, s0, 17
	s_nop 1
	v_writelane_b32 v255, s1, 18
	v_cmp_ge_i32_e64 s[0:1], v17, v170
	v_or_b32_e32 v17, 0x50, v0
	s_nop 0
	v_writelane_b32 v255, s0, 19
	s_nop 1
	v_writelane_b32 v255, s1, 20
	v_cmp_le_i32_e64 s[0:1], v17, v170
	s_nop 1
	v_writelane_b32 v255, s0, 21
	s_nop 1
	v_writelane_b32 v255, s1, 22
	v_cmp_ge_i32_e64 s[0:1], v17, v170
	v_or_b32_e32 v17, 0x51, v0
	s_nop 0
	v_writelane_b32 v255, s0, 23
	s_nop 1
	v_writelane_b32 v255, s1, 24
	v_cmp_le_i32_e64 s[0:1], v17, v170
	s_nop 1
	v_writelane_b32 v255, s0, 25
	s_nop 1
	v_writelane_b32 v255, s1, 26
	v_cmp_ge_i32_e64 s[0:1], v17, v170
	v_or_b32_e32 v17, 0x52, v0
	s_nop 0
	v_writelane_b32 v255, s0, 27
	s_nop 1
	v_writelane_b32 v255, s1, 28
	v_cmp_le_i32_e64 s[0:1], v17, v170
	s_nop 1
	v_writelane_b32 v255, s0, 29
	s_nop 1
	v_writelane_b32 v255, s1, 30
	v_cmp_ge_i32_e64 s[0:1], v17, v170
	v_or_b32_e32 v17, 0x53, v0
	s_nop 0
	v_writelane_b32 v255, s0, 31
	s_nop 1
	v_writelane_b32 v255, s1, 32
	v_cmp_le_i32_e64 s[0:1], v17, v170
	s_nop 1
	v_writelane_b32 v255, s0, 33
	s_nop 1
	v_writelane_b32 v255, s1, 34
	v_cmp_ge_i32_e64 s[0:1], v17, v170
	v_or_b32_e32 v17, 0x58, v0
	s_nop 0
	v_writelane_b32 v255, s0, 35
	s_nop 1
	v_writelane_b32 v255, s1, 36
	v_cmp_le_i32_e64 s[0:1], v17, v170
	s_nop 1
	v_writelane_b32 v255, s0, 37
	s_nop 1
	v_writelane_b32 v255, s1, 38
	v_cmp_ge_i32_e64 s[0:1], v17, v170
	v_or_b32_e32 v17, 0x59, v0
	s_nop 0
	v_writelane_b32 v255, s0, 39
	s_nop 1
	v_writelane_b32 v255, s1, 40
	v_cmp_le_i32_e64 s[0:1], v17, v170
	s_nop 1
	v_writelane_b32 v255, s0, 41
	s_nop 1
	v_writelane_b32 v255, s1, 42
	v_cmp_ge_i32_e64 s[0:1], v17, v170
	v_or_b32_e32 v17, 0x5a, v0
	s_nop 0
	v_writelane_b32 v255, s0, 43
	s_nop 1
	v_writelane_b32 v255, s1, 44
	v_cmp_le_i32_e64 s[0:1], v17, v170
	s_nop 1
	v_writelane_b32 v255, s0, 45
	s_nop 1
	v_writelane_b32 v255, s1, 46
	v_cmp_ge_i32_e64 s[0:1], v17, v170
	v_or_b32_e32 v17, 0x5b, v0
	v_cmp_le_i32_e64 s[24:25], v17, v170
	v_writelane_b32 v255, s0, 47
	v_cmp_ge_i32_e64 s[26:27], v17, v170
	s_nop 0
	v_writelane_b32 v255, s1, 48
	v_cmp_le_i32_e64 s[0:1], v16, v170
	v_and_b32_e32 v222, 32, v168
	v_lshlrev_b32_e32 v222, 9, v222
	v_lshl_add_u32 v222, v221, 3, v222
	v_and_b32_e32 v223, 64, v168
	v_lshl_add_u32 v222, v223, 16, v222
	v_add_co_u32_e32 v216, vcc, s33, v222
	v_mov_b32_e32 v217, s18
	s_nop 1
	v_addc_co_u32_e32 v217, vcc, 0, v217, vcc
	v_add_u32_e32 v250, 0xcc00, v220
	v_lshl_add_u32 v226, v168, 4, v250
	v_lshl_add_u32 v226, v221, 3, v226
	v_lshl_add_u32 v227, v170, 2, v250
	v_lshl_add_u32 v233, v168, 2, v250
	v_add_u32_e32 v233, v233, v128
	v_add_u32_e32 v250, 0x400, v250
	v_add_u32_e32 v250, v250, v128
	s_branch .LBB0_2101

.LBB0_2101:
	s_ashr_i32 s12, s13, 3
	s_lshl_b32 s14, s12, 7
	v_add_u32_e32 v0, s14, v170
	v_ashrrev_i32_e32 v1, 31, v0
	v_readlane_b32 s16, v252, 47
	v_writelane_b32 v255, s13, 49
	s_and_b32 s13, s13, 7
	v_lshlrev_b64 v[0:1], 11, v[0:1]
	v_readlane_b32 s17, v252, 48
	v_readlane_b32 s22, v252, 12
	v_readlane_b32 s23, v252, 13
	v_lshl_add_u64 v[0:1], s[16:17], 0, v[0:1]
	s_lshl_b32 s22, s13, 8
	v_lshl_add_u64 v[0:1], v[0:1], 0, s[22:23]
	v_lshlrev_b32_e32 v2, 1, v172
	v_mov_b32_e32 v3, v129
	v_lshl_add_u64 v[0:1], v[0:1], 0, v[2:3]
	global_load_dwordx4 v[130:133], v[0:1], off
	global_load_dwordx4 v[134:137], v[0:1], off offset:32
	global_load_dwordx4 v[138:141], v[0:1], off offset:64
	global_load_dwordx4 v[142:145], v[0:1], off offset:96
	global_load_dwordx4 v[146:149], v[0:1], off offset:128
	global_load_dwordx4 v[150:153], v[0:1], off offset:160
	global_load_dwordx4 v[154:157], v[0:1], off offset:192
	global_load_dwordx4 v[158:161], v[0:1], off offset:224
	v_or_b32_e32 v0, s14, v173
	v_ashrrev_i32_e32 v1, 31, v0
	v_readlane_b32 s16, v252, 45
	v_lshlrev_b64 v[0:1], 11, v[0:1]
	v_readlane_b32 s17, v252, 46
	s_mov_b32 s15, 0x10000
	s_lshl_b32 s13, s13, 2
	v_lshl_add_u64 v[0:1], s[16:17], 0, v[0:1]
	v_lshl_add_u64 v[0:1], v[0:1], 0, s[22:23]
	v_lshl_add_u64 v[64:65], v[0:1], 0, v[2:3]
	v_add_co_u32_e32 v66, vcc, s15, v64
	s_mov_b32 s15, 0x20000
	s_nop 0
	v_addc_co_u32_e32 v67, vcc, 0, v65, vcc
	v_add_co_u32_e32 v68, vcc, s15, v64
	s_mov_b32 s15, 0x30000
	s_nop 0
	v_addc_co_u32_e32 v69, vcc, 0, v65, vcc
	v_add_co_u32_e32 v70, vcc, s15, v64
	v_writelane_b32 v255, s13, 50
	s_nop 0
	v_addc_co_u32_e32 v71, vcc, 0, v65, vcc
	s_ashr_i32 s13, s12, 31
	s_lshl_b64 s[20:21], s[12:13], 19
	v_readlane_b32 s16, v252, 43
	s_add_u32 s15, s16, s20
	v_writelane_b32 v255, s15, 51
	v_readlane_b32 s17, v252, 44
	v_writelane_b32 v255, s20, 52
	s_addc_u32 s15, s17, s21
	s_lshl_b64 s[16:17], s[12:13], 20
	v_writelane_b32 v255, s21, 53
	v_readlane_b32 s20, v252, 49
	v_writelane_b32 v255, s15, 54
	v_readlane_b32 s21, v252, 50
	s_add_u32 s15, s20, s16
	v_writelane_b32 v255, s15, 55
	s_addc_u32 s15, s21, s17
	v_writelane_b32 v255, s15, 56
	s_mov_b32 s19, 0
	s_lshl_b64 s[12:13], s[12:13], 13
	global_load_dwordx4 v[76:79], v[64:65], off
	global_load_dwordx4 v[80:83], v[66:67], off
	global_load_dwordx4 v[84:87], v[68:69], off
	global_load_dwordx4 v[88:91], v[70:71], off
	global_load_dwordx4 v[92:95], v[64:65], off offset:32
	global_load_dwordx4 v[96:99], v[66:67], off offset:32
	global_load_dwordx4 v[100:103], v[68:69], off offset:32
	global_load_dwordx4 v[104:107], v[70:71], off offset:32
	global_load_dwordx4 v[108:111], v[64:65], off offset:64
	global_load_dwordx4 v[112:115], v[66:67], off offset:64
	global_load_dwordx4 v[116:119], v[68:69], off offset:64
	global_load_dwordx4 v[120:123], v[70:71], off offset:64
	global_load_dwordx4 v[124:127], v[64:65], off offset:96
	global_load_dwordx4 v[72:75], v[66:67], off offset:96
	global_load_dwordx4 v[212:215], v[68:69], off offset:96
	global_load_dwordx4 v[222:225], v[70:71], off offset:96
	global_load_dwordx4 v[234:237], v[64:65], off offset:128
	global_load_dwordx4 v[238:241], v[66:67], off offset:128
	global_load_dwordx4 v[242:245], v[68:69], off offset:128
	global_load_dwordx4 v[246:249], v[70:71], off offset:128
	s_waitcnt vmcnt(19)
	v_mfma_f32_32x32x16_bf16 v[0:15], v[76:79], v[130:133], 0
	global_load_dwordx4 v[76:79], v[64:65], off offset:160
	s_waitcnt vmcnt(19)
	v_mfma_f32_32x32x16_bf16 v[16:31], v[80:83], v[130:133], 0
	global_load_dwordx4 v[80:83], v[66:67], off offset:160
	s_waitcnt vmcnt(19)
	v_mfma_f32_32x32x16_bf16 v[32:47], v[84:87], v[130:133], 0
	global_load_dwordx4 v[84:87], v[68:69], off offset:160
	s_waitcnt vmcnt(19)
	v_mfma_f32_32x32x16_bf16 v[48:63], v[88:91], v[130:133], 0
	global_load_dwordx4 v[88:91], v[70:71], off offset:160
	s_waitcnt vmcnt(19)
	v_mfma_f32_32x32x16_bf16 v[0:15], v[92:95], v[134:137], v[0:15]
	global_load_dwordx4 v[92:95], v[64:65], off offset:192
	s_waitcnt vmcnt(19)
	v_mfma_f32_32x32x16_bf16 v[16:31], v[96:99], v[134:137], v[16:31]
	global_load_dwordx4 v[96:99], v[66:67], off offset:192
	s_waitcnt vmcnt(19)
	v_mfma_f32_32x32x16_bf16 v[32:47], v[100:103], v[134:137], v[32:47]
	global_load_dwordx4 v[100:103], v[68:69], off offset:192
	s_waitcnt vmcnt(19)
	v_mfma_f32_32x32x16_bf16 v[48:63], v[104:107], v[134:137], v[48:63]
	global_load_dwordx4 v[104:107], v[70:71], off offset:192
	s_waitcnt vmcnt(19)
	v_mfma_f32_32x32x16_bf16 v[0:15], v[108:111], v[138:141], v[0:15]
	global_load_dwordx4 v[108:111], v[64:65], off offset:224
	s_waitcnt vmcnt(19)
	v_mfma_f32_32x32x16_bf16 v[16:31], v[112:115], v[138:141], v[16:31]
	global_load_dwordx4 v[112:115], v[66:67], off offset:224
	s_waitcnt vmcnt(19)
	v_mfma_f32_32x32x16_bf16 v[32:47], v[116:119], v[138:141], v[32:47]
	global_load_dwordx4 v[116:119], v[68:69], off offset:224
	s_waitcnt vmcnt(19)
	v_mfma_f32_32x32x16_bf16 v[48:63], v[120:123], v[138:141], v[48:63]
	global_load_dwordx4 v[120:123], v[70:71], off offset:224
	s_waitcnt vmcnt(19)
	v_mfma_f32_32x32x16_bf16 v[0:15], v[124:127], v[142:145], v[0:15]
	s_waitcnt vmcnt(18)
	v_mfma_f32_32x32x16_bf16 v[16:31], v[72:75], v[142:145], v[16:31]
	s_waitcnt vmcnt(17)
	v_mfma_f32_32x32x16_bf16 v[32:47], v[212:215], v[142:145], v[32:47]
	s_waitcnt vmcnt(16)
	v_mfma_f32_32x32x16_bf16 v[48:63], v[222:225], v[142:145], v[48:63]
	s_waitcnt vmcnt(15)
	v_mfma_f32_32x32x16_bf16 v[0:15], v[234:237], v[146:149], v[0:15]
	s_waitcnt vmcnt(14)
	v_mfma_f32_32x32x16_bf16 v[16:31], v[238:241], v[146:149], v[16:31]
	s_waitcnt vmcnt(13)
	v_mfma_f32_32x32x16_bf16 v[32:47], v[242:245], v[146:149], v[32:47]
	s_waitcnt vmcnt(12)
	v_mfma_f32_32x32x16_bf16 v[48:63], v[246:249], v[146:149], v[48:63]
	s_waitcnt vmcnt(11)
	v_mfma_f32_32x32x16_bf16 v[0:15], v[76:79], v[150:153], v[0:15]
	s_waitcnt vmcnt(10)
	v_mfma_f32_32x32x16_bf16 v[16:31], v[80:83], v[150:153], v[16:31]
	s_waitcnt vmcnt(9)
	v_mfma_f32_32x32x16_bf16 v[32:47], v[84:87], v[150:153], v[32:47]
	s_waitcnt vmcnt(8)
	v_mfma_f32_32x32x16_bf16 v[48:63], v[88:91], v[150:153], v[48:63]
	s_waitcnt vmcnt(7)
	v_mfma_f32_32x32x16_bf16 v[0:15], v[92:95], v[154:157], v[0:15]
	s_waitcnt vmcnt(6)
	v_mfma_f32_32x32x16_bf16 v[16:31], v[96:99], v[154:157], v[16:31]
	s_waitcnt vmcnt(5)
	v_mfma_f32_32x32x16_bf16 v[32:47], v[100:103], v[154:157], v[32:47]
	s_waitcnt vmcnt(4)
	v_mfma_f32_32x32x16_bf16 v[48:63], v[104:107], v[154:157], v[48:63]
	s_waitcnt vmcnt(3)
	v_mfma_f32_32x32x16_bf16 v[0:15], v[108:111], v[158:161], v[0:15]
	s_waitcnt vmcnt(2)
	v_mfma_f32_32x32x16_bf16 v[16:31], v[112:115], v[158:161], v[16:31]
	s_waitcnt vmcnt(1)
	v_mfma_f32_32x32x16_bf16 v[32:47], v[116:119], v[158:161], v[32:47]
	s_waitcnt vmcnt(0)
	v_mfma_f32_32x32x16_bf16 v[48:63], v[120:123], v[158:161], v[48:63]
	v_add_u32_e32 v64, s14, v200
	v_ashrrev_i32_e32 v65, 31, v64
	v_readlane_b32 s14, v252, 41
	v_lshlrev_b64 v[64:65], 12, v[64:65]
	v_readlane_b32 s15, v252, 42
	s_nop 1
	v_lshl_add_u64 v[184:185], s[14:15], 0, v[64:65]
	s_branch .LBB0_2103
.LBB0_2102:
	v_readlane_b32 s22, v252, 12
	v_readlane_b32 s23, v252, 13
	v_lshlrev_b32_e32 v96, 1, v173
	s_lshl_b64 s[14:15], s[22:23], 2
	v_readlane_b32 s16, v252, 51
	v_lshl_or_b32 v96, s22, 7, v96
	v_mov_b32_e32 v97, v129
	s_add_u32 s14, s16, s14
	v_readlane_b32 s16, v252, 52
	v_lshl_add_u64 v[112:113], v[184:185], 0, v[96:97]
	s_addc_u32 s15, s16, s15
	global_load_dword v118, v129, s[14:15]
	v_readlane_b32 s19, v255, 57
	v_add_u32_e32 v245, 0x2000, v205
	ds_read2_b64 v[186:189], v205 offset1:2
	ds_read2_b64 v[190:193], v205 offset0:4 offset1:6
	ds_read2_b64 v[194:197], v245 offset0:64 offset1:66
	ds_read2_b64 v[206:209], v245 offset0:68 offset1:70
	s_add_i32 s19, s19, 1
	s_mov_b64 s[14:15], 0x1000
	v_lshl_add_u64 v[100:101], v[112:113], 0, s[14:15]
	s_mov_b64 s[14:15], 0x3000
	v_lshl_add_u64 v[102:103], v[112:113], 0, s[14:15]
	s_mov_b64 s[14:15], 0x9000
	v_lshl_add_u64 v[104:105], v[112:113], 0, s[14:15]
	s_mov_b64 s[14:15], 0xb000
	v_lshl_add_u64 v[106:107], v[112:113], 0, s[14:15]
	s_mov_b64 s[14:15], 0x11000
	v_lshl_add_u64 v[108:109], v[112:113], 0, s[14:15]
	s_mov_b64 s[14:15], 0x13000
	v_lshl_add_u64 v[110:111], v[112:113], 0, s[14:15]
	s_mov_b64 s[14:15], 0x19000
	v_lshl_add_u64 v[114:115], v[112:113], 0, s[14:15]
	s_mov_b64 s[14:15], 0x1b000
	v_lshl_add_u64 v[116:117], v[112:113], 0, s[14:15]
	global_load_ushort v96, v[100:101], off offset:-4096
	global_load_ushort v97, v[100:101], off
	global_load_ushort v98, v[102:103], off offset:-4096
	global_load_ushort v99, v[102:103], off
	global_load_ushort v119, v[104:105], off offset:-4096
	global_load_ushort v120, v[104:105], off
	global_load_ushort v121, v[106:107], off offset:-4096
	global_load_ushort v122, v[106:107], off
	global_load_ushort v123, v[108:109], off offset:-4096
	global_load_ushort v124, v[108:109], off
	global_load_ushort v125, v[110:111], off offset:-4096
	global_load_ushort v126, v[110:111], off
	global_load_ushort v127, v[114:115], off offset:-4096
	global_load_ushort v212, v[114:115], off
	global_load_ushort v213, v[116:117], off offset:-4096
	global_load_ushort v214, v[116:117], off
	global_load_ushort v215, v[100:101], off offset:-4032
	global_load_ushort v222, v[100:101], off offset:64
	global_load_ushort v223, v[102:103], off offset:-4032
	global_load_ushort v224, v[102:103], off offset:64
	global_load_ushort v225, v[104:105], off offset:-4032
	global_load_ushort v234, v[104:105], off offset:64
	global_load_ushort v235, v[106:107], off offset:-4032
	global_load_ushort v236, v[106:107], off offset:64
	global_load_ushort v237, v[108:109], off offset:-4032
	global_load_ushort v238, v[108:109], off offset:64
	global_load_ushort v239, v[110:111], off offset:-4032
	global_load_ushort v240, v[110:111], off offset:64
	global_load_ushort v241, v[114:115], off offset:-4032
	global_load_ushort v242, v[114:115], off offset:64
	global_load_ushort v243, v[116:117], off offset:-4032
	global_load_ushort v244, v[116:117], off offset:64
	s_cmp_eq_u32 s19, 4
	s_waitcnt lgkmcnt(0)
	s_waitcnt vmcnt(28)
	v_lshlrev_b32_e32 v96, 16, v96
	v_lshlrev_b32_e32 v97, 16, v97
	v_lshlrev_b32_e32 v98, 16, v98
	v_lshlrev_b32_e32 v99, 16, v99
	v_lshlrev_b32_e32 v246, 16, v186
	v_and_b32_e32 v247, 0xffff0000, v186
	v_lshlrev_b32_e32 v248, 16, v187
	v_and_b32_e32 v249, 0xffff0000, v187
	v_fmac_f32_e32 v80, v118, v246
	v_fmac_f32_e32 v81, v118, v247
	v_fmac_f32_e32 v82, v118, v248
	v_fmac_f32_e32 v83, v118, v249
	v_mul_f32_e32 v246, 0xbfb8aa3b, v96
	v_mul_f32_e32 v247, 0xbfb8aa3b, v97
	v_mul_f32_e32 v248, 0xbfb8aa3b, v98
	v_mul_f32_e32 v249, 0xbfb8aa3b, v99
	v_exp_f32_e32 v246, v246
	v_exp_f32_e32 v247, v247
	v_exp_f32_e32 v248, v248
	v_exp_f32_e32 v249, v249
	v_add_f32_e32 v246, 1.0, v246
	v_add_f32_e32 v247, 1.0, v247
	v_add_f32_e32 v248, 1.0, v248
	v_add_f32_e32 v249, 1.0, v249
	v_rcp_f32_e32 v246, v246
	v_rcp_f32_e32 v247, v247
	v_rcp_f32_e32 v248, v248
	v_rcp_f32_e32 v249, v249
	v_mul_f32_e32 v96, v96, v246
	v_mul_f32_e32 v97, v97, v247
	v_mul_f32_e32 v98, v98, v248
	v_mul_f32_e32 v99, v99, v249
	v_mul_f32_e32 v80, v80, v96
	v_mul_f32_e32 v81, v81, v97
	v_mul_f32_e32 v82, v82, v98
	v_mul_f32_e32 v83, v83, v99
	v_cvt_pk_bf16_f32 v80, v80, v80
	v_cvt_pk_bf16_f32 v81, v81, v81
	v_cvt_pk_bf16_f32 v82, v82, v82
	v_cvt_pk_bf16_f32 v83, v83, v83
	global_store_short v[100:101], v80, off offset:-4096
	global_store_short v[100:101], v81, off
	global_store_short v[102:103], v82, off offset:-4096
	global_store_short v[102:103], v83, off
	s_waitcnt vmcnt(28)
	v_lshlrev_b32_e32 v119, 16, v119
	v_lshlrev_b32_e32 v120, 16, v120
	v_lshlrev_b32_e32 v121, 16, v121
	v_lshlrev_b32_e32 v122, 16, v122
	v_lshlrev_b32_e32 v246, 16, v188
	v_and_b32_e32 v247, 0xffff0000, v188
	v_lshlrev_b32_e32 v248, 16, v189
	v_and_b32_e32 v249, 0xffff0000, v189
	v_fmac_f32_e32 v84, v118, v246
	v_fmac_f32_e32 v85, v118, v247
	v_fmac_f32_e32 v86, v118, v248
	v_fmac_f32_e32 v87, v118, v249
	v_mul_f32_e32 v246, 0xbfb8aa3b, v119
	v_mul_f32_e32 v247, 0xbfb8aa3b, v120
	v_mul_f32_e32 v248, 0xbfb8aa3b, v121
	v_mul_f32_e32 v249, 0xbfb8aa3b, v122
	v_exp_f32_e32 v246, v246
	v_exp_f32_e32 v247, v247
	v_exp_f32_e32 v248, v248
	v_exp_f32_e32 v249, v249
	v_add_f32_e32 v246, 1.0, v246
	v_add_f32_e32 v247, 1.0, v247
	v_add_f32_e32 v248, 1.0, v248
	v_add_f32_e32 v249, 1.0, v249
	v_rcp_f32_e32 v246, v246
	v_rcp_f32_e32 v247, v247
	v_rcp_f32_e32 v248, v248
	v_rcp_f32_e32 v249, v249
	v_mul_f32_e32 v119, v119, v246
	v_mul_f32_e32 v120, v120, v247
	v_mul_f32_e32 v121, v121, v248
	v_mul_f32_e32 v122, v122, v249
	v_mul_f32_e32 v84, v84, v119
	v_mul_f32_e32 v85, v85, v120
	v_mul_f32_e32 v86, v86, v121
	v_mul_f32_e32 v87, v87, v122
	v_cvt_pk_bf16_f32 v84, v84, v84
	v_cvt_pk_bf16_f32 v85, v85, v85
	v_cvt_pk_bf16_f32 v86, v86, v86
	v_cvt_pk_bf16_f32 v87, v87, v87
	global_store_short v[104:105], v84, off offset:-4096
	global_store_short v[104:105], v85, off
	global_store_short v[106:107], v86, off offset:-4096
	global_store_short v[106:107], v87, off
	s_waitcnt vmcnt(28)
	v_lshlrev_b32_e32 v123, 16, v123
	v_lshlrev_b32_e32 v124, 16, v124
	v_lshlrev_b32_e32 v125, 16, v125
	v_lshlrev_b32_e32 v126, 16, v126
	v_lshlrev_b32_e32 v246, 16, v190
	v_and_b32_e32 v247, 0xffff0000, v190
	v_lshlrev_b32_e32 v248, 16, v191
	v_and_b32_e32 v249, 0xffff0000, v191
	v_fmac_f32_e32 v88, v118, v246
	v_fmac_f32_e32 v89, v118, v247
	v_fmac_f32_e32 v90, v118, v248
	v_fmac_f32_e32 v91, v118, v249
	v_mul_f32_e32 v246, 0xbfb8aa3b, v123
	v_mul_f32_e32 v247, 0xbfb8aa3b, v124
	v_mul_f32_e32 v248, 0xbfb8aa3b, v125
	v_mul_f32_e32 v249, 0xbfb8aa3b, v126
	v_exp_f32_e32 v246, v246
	v_exp_f32_e32 v247, v247
	v_exp_f32_e32 v248, v248
	v_exp_f32_e32 v249, v249
	v_add_f32_e32 v246, 1.0, v246
	v_add_f32_e32 v247, 1.0, v247
	v_add_f32_e32 v248, 1.0, v248
	v_add_f32_e32 v249, 1.0, v249
	v_rcp_f32_e32 v246, v246
	v_rcp_f32_e32 v247, v247
	v_rcp_f32_e32 v248, v248
	v_rcp_f32_e32 v249, v249
	v_mul_f32_e32 v123, v123, v246
	v_mul_f32_e32 v124, v124, v247
	v_mul_f32_e32 v125, v125, v248
	v_mul_f32_e32 v126, v126, v249
	v_mul_f32_e32 v88, v88, v123
	v_mul_f32_e32 v89, v89, v124
	v_mul_f32_e32 v90, v90, v125
	v_mul_f32_e32 v91, v91, v126
	v_cvt_pk_bf16_f32 v88, v88, v88
	v_cvt_pk_bf16_f32 v89, v89, v89
	v_cvt_pk_bf16_f32 v90, v90, v90
	v_cvt_pk_bf16_f32 v91, v91, v91
	global_store_short v[108:109], v88, off offset:-4096
	global_store_short v[108:109], v89, off
	global_store_short v[110:111], v90, off offset:-4096
	global_store_short v[110:111], v91, off
	s_waitcnt vmcnt(28)
	v_lshlrev_b32_e32 v127, 16, v127
	v_lshlrev_b32_e32 v212, 16, v212
	v_lshlrev_b32_e32 v213, 16, v213
	v_lshlrev_b32_e32 v214, 16, v214
	v_lshlrev_b32_e32 v246, 16, v192
	v_and_b32_e32 v247, 0xffff0000, v192
	v_lshlrev_b32_e32 v248, 16, v193
	v_and_b32_e32 v249, 0xffff0000, v193
	v_fmac_f32_e32 v92, v118, v246
	v_fmac_f32_e32 v93, v118, v247
	v_fmac_f32_e32 v94, v118, v248
	v_fmac_f32_e32 v95, v118, v249
	v_mul_f32_e32 v246, 0xbfb8aa3b, v127
	v_mul_f32_e32 v247, 0xbfb8aa3b, v212
	v_mul_f32_e32 v248, 0xbfb8aa3b, v213
	v_mul_f32_e32 v249, 0xbfb8aa3b, v214
	v_exp_f32_e32 v246, v246
	v_exp_f32_e32 v247, v247
	v_exp_f32_e32 v248, v248
	v_exp_f32_e32 v249, v249
	v_add_f32_e32 v246, 1.0, v246
	v_add_f32_e32 v247, 1.0, v247
	v_add_f32_e32 v248, 1.0, v248
	v_add_f32_e32 v249, 1.0, v249
	v_rcp_f32_e32 v246, v246
	v_rcp_f32_e32 v247, v247
	v_rcp_f32_e32 v248, v248
	v_rcp_f32_e32 v249, v249
	v_mul_f32_e32 v127, v127, v246
	v_mul_f32_e32 v212, v212, v247
	v_mul_f32_e32 v213, v213, v248
	v_mul_f32_e32 v214, v214, v249
	v_mul_f32_e32 v92, v92, v127
	v_mul_f32_e32 v93, v93, v212
	v_mul_f32_e32 v94, v94, v213
	v_mul_f32_e32 v95, v95, v214
	v_cvt_pk_bf16_f32 v92, v92, v92
	v_cvt_pk_bf16_f32 v93, v93, v93
	v_cvt_pk_bf16_f32 v94, v94, v94
	v_cvt_pk_bf16_f32 v95, v95, v95
	global_store_short v[114:115], v92, off offset:-4096
	global_store_short v[114:115], v93, off
	global_store_short v[116:117], v94, off offset:-4096
	global_store_short v[116:117], v95, off
	s_waitcnt vmcnt(28)
	v_lshlrev_b32_e32 v215, 16, v215
	v_lshlrev_b32_e32 v222, 16, v222
	v_lshlrev_b32_e32 v223, 16, v223
	v_lshlrev_b32_e32 v224, 16, v224
	v_lshlrev_b32_e32 v246, 16, v194
	v_and_b32_e32 v247, 0xffff0000, v194
	v_lshlrev_b32_e32 v248, 16, v195
	v_and_b32_e32 v249, 0xffff0000, v195
	v_fmac_f32_e32 v64, v118, v246
	v_fmac_f32_e32 v65, v118, v247
	v_fmac_f32_e32 v66, v118, v248
	v_fmac_f32_e32 v67, v118, v249
	v_mul_f32_e32 v246, 0xbfb8aa3b, v215
	v_mul_f32_e32 v247, 0xbfb8aa3b, v222
	v_mul_f32_e32 v248, 0xbfb8aa3b, v223
	v_mul_f32_e32 v249, 0xbfb8aa3b, v224
	v_exp_f32_e32 v246, v246
	v_exp_f32_e32 v247, v247
	v_exp_f32_e32 v248, v248
	v_exp_f32_e32 v249, v249
	v_add_f32_e32 v246, 1.0, v246
	v_add_f32_e32 v247, 1.0, v247
	v_add_f32_e32 v248, 1.0, v248
	v_add_f32_e32 v249, 1.0, v249
	v_rcp_f32_e32 v246, v246
	v_rcp_f32_e32 v247, v247
	v_rcp_f32_e32 v248, v248
	v_rcp_f32_e32 v249, v249
	v_mul_f32_e32 v215, v215, v246
	v_mul_f32_e32 v222, v222, v247
	v_mul_f32_e32 v223, v223, v248
	v_mul_f32_e32 v224, v224, v249
	v_mul_f32_e32 v64, v64, v215
	v_mul_f32_e32 v65, v65, v222
	v_mul_f32_e32 v66, v66, v223
	v_mul_f32_e32 v67, v67, v224
	v_cvt_pk_bf16_f32 v64, v64, v64
	v_cvt_pk_bf16_f32 v65, v65, v65
	v_cvt_pk_bf16_f32 v66, v66, v66
	v_cvt_pk_bf16_f32 v67, v67, v67
	global_store_short v[100:101], v64, off offset:-4032
	global_store_short v[100:101], v65, off offset:64
	global_store_short v[102:103], v66, off offset:-4032
	global_store_short v[102:103], v67, off offset:64
	s_waitcnt vmcnt(28)
	v_lshlrev_b32_e32 v225, 16, v225
	v_lshlrev_b32_e32 v234, 16, v234
	v_lshlrev_b32_e32 v235, 16, v235
	v_lshlrev_b32_e32 v236, 16, v236
	v_lshlrev_b32_e32 v246, 16, v196
	v_and_b32_e32 v247, 0xffff0000, v196
	v_lshlrev_b32_e32 v248, 16, v197
	v_and_b32_e32 v249, 0xffff0000, v197
	v_fmac_f32_e32 v68, v118, v246
	v_fmac_f32_e32 v69, v118, v247
	v_fmac_f32_e32 v70, v118, v248
	v_fmac_f32_e32 v71, v118, v249
	v_mul_f32_e32 v246, 0xbfb8aa3b, v225
	v_mul_f32_e32 v247, 0xbfb8aa3b, v234
	v_mul_f32_e32 v248, 0xbfb8aa3b, v235
	v_mul_f32_e32 v249, 0xbfb8aa3b, v236
	v_exp_f32_e32 v246, v246
	v_exp_f32_e32 v247, v247
	v_exp_f32_e32 v248, v248
	v_exp_f32_e32 v249, v249
	v_add_f32_e32 v246, 1.0, v246
	v_add_f32_e32 v247, 1.0, v247
	v_add_f32_e32 v248, 1.0, v248
	v_add_f32_e32 v249, 1.0, v249
	v_rcp_f32_e32 v246, v246
	v_rcp_f32_e32 v247, v247
	v_rcp_f32_e32 v248, v248
	v_rcp_f32_e32 v249, v249
	v_mul_f32_e32 v225, v225, v246
	v_mul_f32_e32 v234, v234, v247
	v_mul_f32_e32 v235, v235, v248
	v_mul_f32_e32 v236, v236, v249
	v_mul_f32_e32 v68, v68, v225
	v_mul_f32_e32 v69, v69, v234
	v_mul_f32_e32 v70, v70, v235
	v_mul_f32_e32 v71, v71, v236
	v_cvt_pk_bf16_f32 v68, v68, v68
	v_cvt_pk_bf16_f32 v69, v69, v69
	v_cvt_pk_bf16_f32 v70, v70, v70
	v_cvt_pk_bf16_f32 v71, v71, v71
	global_store_short v[104:105], v68, off offset:-4032
	global_store_short v[104:105], v69, off offset:64
	global_store_short v[106:107], v70, off offset:-4032
	global_store_short v[106:107], v71, off offset:64
	s_waitcnt vmcnt(28)
	v_lshlrev_b32_e32 v237, 16, v237
	v_lshlrev_b32_e32 v238, 16, v238
	v_lshlrev_b32_e32 v239, 16, v239
	v_lshlrev_b32_e32 v240, 16, v240
	v_lshlrev_b32_e32 v246, 16, v206
	v_and_b32_e32 v247, 0xffff0000, v206
	v_lshlrev_b32_e32 v248, 16, v207
	v_and_b32_e32 v249, 0xffff0000, v207
	v_fmac_f32_e32 v72, v118, v246
	v_fmac_f32_e32 v73, v118, v247
	v_fmac_f32_e32 v74, v118, v248
	v_fmac_f32_e32 v75, v118, v249
	v_mul_f32_e32 v246, 0xbfb8aa3b, v237
	v_mul_f32_e32 v247, 0xbfb8aa3b, v238
	v_mul_f32_e32 v248, 0xbfb8aa3b, v239
	v_mul_f32_e32 v249, 0xbfb8aa3b, v240
	v_exp_f32_e32 v246, v246
	v_exp_f32_e32 v247, v247
	v_exp_f32_e32 v248, v248
	v_exp_f32_e32 v249, v249
	v_add_f32_e32 v246, 1.0, v246
	v_add_f32_e32 v247, 1.0, v247
	v_add_f32_e32 v248, 1.0, v248
	v_add_f32_e32 v249, 1.0, v249
	v_rcp_f32_e32 v246, v246
	v_rcp_f32_e32 v247, v247
	v_rcp_f32_e32 v248, v248
	v_rcp_f32_e32 v249, v249
	v_mul_f32_e32 v237, v237, v246
	v_mul_f32_e32 v238, v238, v247
	v_mul_f32_e32 v239, v239, v248
	v_mul_f32_e32 v240, v240, v249
	v_mul_f32_e32 v72, v72, v237
	v_mul_f32_e32 v73, v73, v238
	v_mul_f32_e32 v74, v74, v239
	v_mul_f32_e32 v75, v75, v240
	v_cvt_pk_bf16_f32 v72, v72, v72
	v_cvt_pk_bf16_f32 v73, v73, v73
	v_cvt_pk_bf16_f32 v74, v74, v74
	v_cvt_pk_bf16_f32 v75, v75, v75
	global_store_short v[108:109], v72, off offset:-4032
	global_store_short v[108:109], v73, off offset:64
	global_store_short v[110:111], v74, off offset:-4032
	global_store_short v[110:111], v75, off offset:64
	s_waitcnt vmcnt(28)
	v_lshlrev_b32_e32 v241, 16, v241
	v_lshlrev_b32_e32 v242, 16, v242
	v_lshlrev_b32_e32 v243, 16, v243
	v_lshlrev_b32_e32 v244, 16, v244
	v_lshlrev_b32_e32 v246, 16, v208
	v_and_b32_e32 v247, 0xffff0000, v208
	v_lshlrev_b32_e32 v248, 16, v209
	v_and_b32_e32 v249, 0xffff0000, v209
	v_fmac_f32_e32 v76, v118, v246
	v_fmac_f32_e32 v77, v118, v247
	v_fmac_f32_e32 v78, v118, v248
	v_fmac_f32_e32 v79, v118, v249
	v_mul_f32_e32 v246, 0xbfb8aa3b, v241
	v_mul_f32_e32 v247, 0xbfb8aa3b, v242
	v_mul_f32_e32 v248, 0xbfb8aa3b, v243
	v_mul_f32_e32 v249, 0xbfb8aa3b, v244
	v_exp_f32_e32 v246, v246
	v_exp_f32_e32 v247, v247
	v_exp_f32_e32 v248, v248
	v_exp_f32_e32 v249, v249
	v_add_f32_e32 v246, 1.0, v246
	v_add_f32_e32 v247, 1.0, v247
	v_add_f32_e32 v248, 1.0, v248
	v_add_f32_e32 v249, 1.0, v249
	v_rcp_f32_e32 v246, v246
	v_rcp_f32_e32 v247, v247
	v_rcp_f32_e32 v248, v248
	v_rcp_f32_e32 v249, v249
	v_mul_f32_e32 v241, v241, v246
	v_mul_f32_e32 v242, v242, v247
	v_mul_f32_e32 v243, v243, v248
	v_mul_f32_e32 v244, v244, v249
	v_mul_f32_e32 v76, v76, v241
	v_mul_f32_e32 v77, v77, v242
	v_mul_f32_e32 v78, v78, v243
	v_mul_f32_e32 v79, v79, v244
	v_cvt_pk_bf16_f32 v76, v76, v76
	v_cvt_pk_bf16_f32 v77, v77, v77
	v_cvt_pk_bf16_f32 v78, v78, v78
	v_cvt_pk_bf16_f32 v79, v79, v79
	global_store_short v[114:115], v76, off offset:-4032
	global_store_short v[114:115], v77, off offset:64
	global_store_short v[116:117], v78, off offset:-4032
	global_store_short v[116:117], v79, off offset:64
	s_cbranch_scc1 .LBB0_2100
.LBB0_2103:
	v_writelane_b32 v255, s19, 57
	s_nop 0
	v_readlane_b32 s14, v255, 50
	s_add_i32 s22, s19, s14
	s_lshl_b32 s14, s22, 14
	v_readlane_b32 s15, v255, 51
	s_add_u32 s14, s15, s14
	v_readlane_b32 s15, v255, 54
	s_addc_u32 s15, s15, 0
	s_lshl_b64 s[16:17], s[22:23], 14
	v_readlane_b32 s19, v255, 55
	s_add_u32 s16, s19, s16
	v_readlane_b32 s19, v255, 56
	s_addc_u32 s17, s19, s17
	s_lshl_b64 s[20:21], s[22:23], 13
	v_readlane_b32 vcc_lo, v255, 52
	v_readlane_b32 vcc_hi, v255, 53
	s_add_u32 s20, s20, vcc_lo
	s_addc_u32 s21, s21, vcc_hi
	s_lshl_b64 s[20:21], s[20:21], 1
	s_or_b32 s19, s20, 0x80000
	v_readlane_b32 vcc_lo, v252, 49
	v_readlane_b32 vcc_hi, v252, 50
	s_add_u32 s20, vcc_lo, s19
	v_lshl_add_u64 v[64:65], s[14:15], 0, v[176:177]
	s_barrier
	s_addc_u32 s21, vcc_hi, s21
	s_lshl_b32 s100, s22, 7
	s_add_u32 s100, s100, s12
	s_lshl_b32 s100, s100, 2
	s_mov_b32 s101, 0
	v_lshl_add_u64 v[222:223], s[100:101], 0, v[216:217]
	global_load_dwordx2 v[224:225], v[222:223], off
	global_load_dwordx4 v[64:67], v[64:65], off
	v_lshl_add_u64 v[68:69], s[16:17], 0, v[176:177]
	global_load_dwordx4 v[68:71], v[68:69], off
	v_lshl_add_u64 v[72:73], s[20:21], 0, v[176:177]
	global_load_dwordx4 v[72:75], v[72:73], off
	v_lshl_add_u64 v[76:77], s[14:15], 0, v[178:179]
	global_load_dwordx4 v[76:79], v[76:77], off
	v_lshl_add_u64 v[80:81], s[16:17], 0, v[178:179]
	global_load_dwordx4 v[80:83], v[80:81], off
	v_lshl_add_u64 v[84:85], s[20:21], 0, v[178:179]
	global_load_dwordx4 v[84:87], v[84:85], off
	v_lshl_add_u64 v[88:89], s[14:15], 0, v[180:181]
	global_load_dwordx4 v[88:91], v[88:89], off
	v_lshl_add_u64 v[92:93], s[16:17], 0, v[180:181]
	global_load_dwordx4 v[92:95], v[92:93], off
	v_lshl_add_u64 v[96:97], s[20:21], 0, v[180:181]
	global_load_dwordx4 v[96:99], v[96:97], off
	v_lshl_add_u64 v[100:101], s[14:15], 0, v[182:183]
	global_load_dwordx4 v[100:103], v[100:101], off
	v_lshl_add_u64 v[104:105], s[16:17], 0, v[182:183]
	global_load_dwordx4 v[104:107], v[104:105], off
	v_lshl_add_u64 v[108:109], s[20:21], 0, v[182:183]
	global_load_dwordx4 v[108:111], v[108:109], off
	v_writelane_b32 v252, s22, 12
	s_lshl_b32 s19, s22, 7
	s_mov_b64 s[14:15], -1
	v_writelane_b32 v252, s23, 13
	s_mov_b32 s20, 0
	s_waitcnt vmcnt(11)
	ds_write_b64 v226, v[224:225]
	ds_write_b128 v201, v[64:67]
	s_waitcnt vmcnt(10)
	ds_write_b128 v201, v[68:71] offset:17408
	s_waitcnt vmcnt(9)
	ds_write_b128 v201, v[72:75] offset:34816
	s_waitcnt vmcnt(8)
	ds_write_b128 v202, v[76:79]
	s_waitcnt vmcnt(7)
	ds_write_b128 v202, v[80:83] offset:17408
	s_waitcnt vmcnt(6)
	ds_write_b128 v202, v[84:87] offset:34816
	s_waitcnt vmcnt(5)
	ds_write_b128 v203, v[88:91]
	s_waitcnt vmcnt(4)
	ds_write_b128 v203, v[92:95] offset:17408
	s_waitcnt vmcnt(3)
	ds_write_b128 v203, v[96:99] offset:34816
	s_waitcnt vmcnt(2)
	ds_write_b128 v204, v[100:103]
	s_waitcnt vmcnt(1)
	ds_write_b128 v204, v[104:107] offset:17408
	s_waitcnt vmcnt(0)
	ds_write_b128 v204, v[108:111] offset:34816
	v_mov_b32_e32 v78, v129
	v_mov_b32_e32 v79, v129
	v_mov_b32_e32 v64, v129
	v_mov_b32_e32 v65, v129
	v_mov_b32_e32 v66, v129
	v_mov_b32_e32 v67, v129
	v_mov_b32_e32 v68, v129
	v_mov_b32_e32 v69, v129
	v_mov_b32_e32 v70, v129
	v_mov_b32_e32 v71, v129
	v_mov_b32_e32 v72, v129
	v_mov_b32_e32 v73, v129
	v_mov_b32_e32 v74, v129
	v_mov_b32_e32 v75, v129
	v_mov_b32_e32 v76, v129
	v_mov_b32_e32 v77, v129
	v_mov_b64_e32 v[94:95], v[78:79]
	v_mov_b64_e32 v[92:93], v[76:77]
	v_mov_b64_e32 v[90:91], v[74:75]
	v_mov_b64_e32 v[88:89], v[72:73]
	v_mov_b64_e32 v[86:87], v[70:71]
	v_mov_b64_e32 v[84:85], v[68:69]
	v_mov_b64_e32 v[82:83], v[66:67]
	v_mov_b64_e32 v[80:81], v[64:65]
	s_waitcnt lgkmcnt(0)
	s_barrier
	s_branch .LBB0_2105

.LBB0_2105:
	s_lshl_b32 s16, s20, 12
	s_add_i32 s16, s16, s19
	s_or_b32 s16, s12, s16
	s_mov_b32 s17, s13
	s_lshl_b64 s[16:17], s[16:17], 2
	s_add_u32 vcc_lo, s33, s16
	s_addc_u32 vcc_hi, s18, s17
	s_lshl_b32 s100, s20, 9
	v_add_u32_e32 v212, s100, v227
	v_add_u32_e32 v213, s100, v233
	v_add_u32_e32 v214, s100, v250
	s_mulk_i32 s20, 0x4400
	v_add_u32_e32 v190, s20, v199
	ds_read_b32 v206, v212
	ds_read_b128 v[186:189], v190 offset:17408
	ds_read_b128 v[234:237], v190 offset:26112
	ds_read_b128 v[238:241], v190 offset:17440
	ds_read_b128 v[242:245], v190 offset:26144
	ds_read_b128 v[246:249], v190 offset:17472
	s_waitcnt lgkmcnt(4)
	v_mfma_f32_32x32x16_bf16 v[112:127], v[130:133], v[186:189], 0
	ds_read_b128 v[186:189], v190 offset:26176
	s_waitcnt lgkmcnt(4)
	v_mfma_f32_32x32x16_bf16 v[96:111], v[130:133], v[234:237], 0
	ds_read_b128 v[234:237], v190 offset:17504
	s_waitcnt lgkmcnt(4)
	v_mfma_f32_32x32x16_bf16 v[112:127], v[134:137], v[238:241], v[112:127]
	ds_read_b128 v[238:241], v190 offset:26208
	s_waitcnt lgkmcnt(4)
	v_mfma_f32_32x32x16_bf16 v[96:111], v[134:137], v[242:245], v[96:111]
	ds_read_b128 v[242:245], v190 offset:17536
	s_waitcnt lgkmcnt(4)
	v_mfma_f32_32x32x16_bf16 v[112:127], v[138:141], v[246:249], v[112:127]
	ds_read_b128 v[246:249], v190 offset:26240
	s_waitcnt lgkmcnt(4)
	v_mfma_f32_32x32x16_bf16 v[96:111], v[138:141], v[186:189], v[96:111]
	ds_read_b128 v[186:189], v190 offset:17568
	s_waitcnt lgkmcnt(4)
	v_mfma_f32_32x32x16_bf16 v[112:127], v[142:145], v[234:237], v[112:127]
	ds_read_b128 v[234:237], v190 offset:26272
	s_waitcnt lgkmcnt(4)
	v_mfma_f32_32x32x16_bf16 v[96:111], v[142:145], v[238:241], v[96:111]
	ds_read_b128 v[238:241], v190 offset:17600
	s_waitcnt lgkmcnt(4)
	v_mfma_f32_32x32x16_bf16 v[112:127], v[146:149], v[242:245], v[112:127]
	ds_read_b128 v[242:245], v190 offset:26304
	s_waitcnt lgkmcnt(4)
	v_mfma_f32_32x32x16_bf16 v[96:111], v[146:149], v[246:249], v[96:111]
	ds_read_b128 v[246:249], v190 offset:17632
	s_waitcnt lgkmcnt(4)
	v_mfma_f32_32x32x16_bf16 v[112:127], v[150:153], v[186:189], v[112:127]
	ds_read_b128 v[186:189], v190 offset:26336
	s_waitcnt lgkmcnt(4)
	v_mfma_f32_32x32x16_bf16 v[96:111], v[150:153], v[234:237], v[96:111]
	s_waitcnt lgkmcnt(3)
	v_mfma_f32_32x32x16_bf16 v[112:127], v[154:157], v[238:241], v[112:127]
	s_waitcnt lgkmcnt(2)
	v_mfma_f32_32x32x16_bf16 v[96:111], v[154:157], v[242:245], v[96:111]
	s_waitcnt lgkmcnt(1)
	v_mfma_f32_32x32x16_bf16 v[112:127], v[158:161], v[246:249], v[112:127]
	s_waitcnt lgkmcnt(0)
	v_mfma_f32_32x32x16_bf16 v[96:111], v[158:161], v[186:189], v[96:111]
	ds_read_b128 v[186:189], v213
	ds_read_b128 v[190:193], v213 offset:32
	ds_read_b128 v[194:197], v213 offset:64
	s_waitcnt lgkmcnt(2)
	v_mul_f32_e32 v186, 0x3fb8aa3b, v186
	ds_read_b128 v[208:211], v213 offset:96
	v_mul_f32_e32 v187, 0x3fb8aa3b, v187
	v_exp_f32_e32 v186, v186
	v_exp_f32_e32 v187, v187
	v_mul_f32_e32 v188, 0x3fb8aa3b, v188
	v_mul_f32_e32 v189, 0x3fb8aa3b, v189
	s_waitcnt lgkmcnt(2)
	v_mul_f32_e32 v190, 0x3fb8aa3b, v190
	v_mul_f32_e32 v191, 0x3fb8aa3b, v191
	v_mul_f32_e32 v192, 0x3fb8aa3b, v192
	v_mul_f32_e32 v193, 0x3fb8aa3b, v193
	s_waitcnt lgkmcnt(1)
	v_mul_f32_e32 v194, 0x3fb8aa3b, v194
	v_mul_f32_e32 v195, 0x3fb8aa3b, v195
	v_mul_f32_e32 v196, 0x3fb8aa3b, v196
	v_mul_f32_e32 v197, 0x3fb8aa3b, v197
	v_exp_f32_e32 v188, v188
	v_exp_f32_e32 v189, v189
	v_exp_f32_e32 v190, v190
	v_exp_f32_e32 v191, v191
	v_exp_f32_e32 v192, v192
	v_exp_f32_e32 v193, v193
	v_exp_f32_e32 v194, v194
	v_exp_f32_e32 v195, v195
	v_exp_f32_e32 v196, v196
	v_exp_f32_e32 v197, v197
	v_pk_fma_f32 v[64:65], v[96:97], v[186:187], v[64:65]
	v_cndmask_b32_e64 v96, 0, 1, s[4:5]
	v_cndmask_b32_e64 v97, 0, 1, s[6:7]
	v_cndmask_b32_e64 v96, v97, v96, s[14:15]
	v_and_b32_e32 v96, 1, v96
	v_pk_fma_f32 v[90:91], v[122:123], v[196:197], v[90:91]
	v_pk_fma_f32 v[88:89], v[120:121], v[194:195], v[88:89]
	v_pk_fma_f32 v[86:87], v[118:119], v[192:193], v[86:87]
	v_pk_fma_f32 v[84:85], v[116:117], v[190:191], v[84:85]
	v_pk_fma_f32 v[82:83], v[114:115], v[188:189], v[82:83]
	v_pk_fma_f32 v[80:81], v[112:113], v[186:187], v[80:81]
	v_pk_fma_f32 v[74:75], v[106:107], v[196:197], v[74:75]
	v_pk_fma_f32 v[72:73], v[104:105], v[194:195], v[72:73]
	v_pk_fma_f32 v[70:71], v[102:103], v[192:193], v[70:71]
	v_pk_fma_f32 v[68:69], v[100:101], v[190:191], v[68:69]
	v_pk_fma_f32 v[66:67], v[98:99], v[188:189], v[66:67]
	v_cmp_eq_u32_e32 vcc, 1, v96
	s_waitcnt lgkmcnt(0)
	v_mul_f32_e32 v207, 0x3fb8aa3b, v208
	v_exp_f32_e32 v208, v207
	v_mul_f32_e32 v207, 0x3fb8aa3b, v209
	v_exp_f32_e32 v209, v207
	v_mul_f32_e32 v207, 0x3fb8aa3b, v210
	v_exp_f32_e32 v210, v207
	v_mul_f32_e32 v207, 0x3fb8aa3b, v211
	v_exp_f32_e32 v211, v207
	v_pk_fma_f32 v[92:93], v[124:125], v[208:209], v[92:93]
	v_pk_fma_f32 v[76:77], v[108:109], v[208:209], v[76:77]
	v_lshl_add_u64 v[108:109], v[174:175], 0, s[16:17]
	v_pk_fma_f32 v[94:95], v[126:127], v[210:211], v[94:95]
	v_pk_fma_f32 v[78:79], v[110:111], v[210:211], v[78:79]
	v_add_u32_e32 v110, v198, v172
	s_and_saveexec_b64 s[16:17], vcc
	s_cbranch_execz .LBB0_2107
	ds_read_b128 v[100:103], v214
	ds_read_b128 v[96:99], v214 offset:32
	v_readlane_b32 s20, v252, 53
	v_readlane_b32 s21, v252, 54
	v_add_u32_e32 v111, 0x2000, v110
	s_waitcnt lgkmcnt(1)
	v_sub_f32_e32 v100, v206, v100
	v_cndmask_b32_e64 v104, 0, 1, s[20:21]
	v_readlane_b32 s20, v252, 55
	v_readlane_b32 s21, v252, 56
	v_mul_f32_e32 v100, 0x3fb8aa3b, v100
	v_sub_f32_e32 v101, v206, v101
	v_cndmask_b32_e64 v105, 0, 1, s[20:21]
	v_cndmask_b32_e64 v104, v105, v104, s[14:15]
	v_readlane_b32 s20, v252, 57
	v_and_b32_e32 v104, 1, v104
	v_readlane_b32 s21, v252, 58
	v_cmp_eq_u32_e32 vcc, 1, v104
	v_mul_f32_e32 v101, 0x3fb8aa3b, v101
	v_cndmask_b32_e64 v104, 0, 1, s[20:21]
	v_readlane_b32 s20, v252, 59
	v_readlane_b32 s21, v252, 60
	v_cndmask_b32_e32 v100, v232, v100, vcc
	v_sub_f32_e32 v102, v206, v102
	v_cndmask_b32_e64 v105, 0, 1, s[20:21]
	v_cndmask_b32_e64 v104, v105, v104, s[14:15]
	v_readlane_b32 s20, v252, 61
	v_and_b32_e32 v104, 1, v104
	v_readlane_b32 s21, v252, 62
	v_cmp_eq_u32_e32 vcc, 1, v104
	v_mul_f32_e32 v102, 0x3fb8aa3b, v102
	v_cndmask_b32_e64 v104, 0, 1, s[20:21]
	v_readlane_b32 s20, v252, 63
	v_readlane_b32 s21, v253, 0
	v_cndmask_b32_e32 v101, v232, v101, vcc
	v_sub_f32_e32 v103, v206, v103
	v_cndmask_b32_e64 v105, 0, 1, s[20:21]
	v_cndmask_b32_e64 v104, v105, v104, s[14:15]
	v_readlane_b32 s20, v253, 1
	v_and_b32_e32 v104, 1, v104
	v_readlane_b32 s21, v253, 2
	v_cmp_eq_u32_e32 vcc, 1, v104
	v_mul_f32_e32 v103, 0x3fb8aa3b, v103
	v_cndmask_b32_e64 v104, 0, 1, s[20:21]
	v_readlane_b32 s20, v253, 3
	v_readlane_b32 s21, v253, 4
	v_cndmask_b32_e32 v102, v232, v102, vcc
	s_waitcnt lgkmcnt(0)
	v_sub_f32_e32 v96, v206, v96
	v_cndmask_b32_e64 v105, 0, 1, s[20:21]
	v_cndmask_b32_e64 v104, v105, v104, s[14:15]
	v_readlane_b32 s20, v253, 5
	v_and_b32_e32 v104, 1, v104
	v_readlane_b32 s21, v253, 6
	v_cmp_eq_u32_e32 vcc, 1, v104
	v_mul_f32_e32 v96, 0x3fb8aa3b, v96
	v_cndmask_b32_e64 v104, 0, 1, s[20:21]
	v_readlane_b32 s20, v253, 7
	v_readlane_b32 s21, v253, 8
	v_cndmask_b32_e32 v103, v232, v103, vcc
	v_sub_f32_e32 v97, v206, v97
	v_cndmask_b32_e64 v105, 0, 1, s[20:21]
	v_cndmask_b32_e64 v104, v105, v104, s[14:15]
	v_readlane_b32 s20, v253, 9
	v_and_b32_e32 v104, 1, v104
	v_readlane_b32 s21, v253, 10
	v_cmp_eq_u32_e32 vcc, 1, v104
	v_mul_f32_e32 v97, 0x3fb8aa3b, v97
	v_cndmask_b32_e64 v104, 0, 1, s[20:21]
	v_readlane_b32 s20, v253, 11
	v_readlane_b32 s21, v253, 12
	v_cndmask_b32_e32 v96, v232, v96, vcc
	v_sub_f32_e32 v98, v206, v98
	v_cndmask_b32_e64 v105, 0, 1, s[20:21]
	v_cndmask_b32_e64 v104, v105, v104, s[14:15]
	v_readlane_b32 s20, v253, 13
	v_and_b32_e32 v104, 1, v104
	v_readlane_b32 s21, v253, 14
	v_cmp_eq_u32_e32 vcc, 1, v104
	v_mul_f32_e32 v98, 0x3fb8aa3b, v98
	v_cndmask_b32_e64 v104, 0, 1, s[20:21]
	v_readlane_b32 s20, v253, 15
	v_readlane_b32 s21, v253, 16
	v_cndmask_b32_e32 v97, v232, v97, vcc
	v_sub_f32_e32 v99, v206, v99
	v_cndmask_b32_e64 v105, 0, 1, s[20:21]
	v_cndmask_b32_e64 v104, v105, v104, s[14:15]
	v_readlane_b32 s20, v253, 17
	v_and_b32_e32 v104, 1, v104
	v_readlane_b32 s21, v253, 18
	v_cmp_eq_u32_e32 vcc, 1, v104
	v_mul_f32_e32 v99, 0x3fb8aa3b, v99
	v_cndmask_b32_e64 v104, 0, 1, s[20:21]
	v_readlane_b32 s20, v253, 19
	v_readlane_b32 s21, v253, 20
	v_cndmask_b32_e32 v98, v232, v98, vcc
	v_exp_f32_e32 v100, v100
	v_cndmask_b32_e64 v105, 0, 1, s[20:21]
	v_cndmask_b32_e64 v104, v105, v104, s[14:15]
	v_and_b32_e32 v104, 1, v104
	v_cmp_eq_u32_e32 vcc, 1, v104
	v_exp_f32_e32 v101, v101
	v_exp_f32_e32 v102, v102
	v_cndmask_b32_e32 v99, v232, v99, vcc
	v_exp_f32_e32 v103, v103
	v_exp_f32_e32 v96, v96
	v_exp_f32_e32 v97, v97
	v_exp_f32_e32 v98, v98
	v_exp_f32_e32 v99, v99
	v_pk_mul_f32 v[100:101], v[0:1], v[100:101]
	v_pk_mul_f32 v[102:103], v[2:3], v[102:103]
	v_pk_mul_f32 v[96:97], v[4:5], v[96:97]
	v_pk_mul_f32 v[98:99], v[6:7], v[98:99]
	v_cvt_pk_bf16_f32 v100, v100, v101
	v_cvt_pk_bf16_f32 v101, v102, v103
	v_cvt_pk_bf16_f32 v102, v96, v97
	v_cvt_pk_bf16_f32 v103, v98, v99
	ds_read2_b64 v[104:107], v110 offset1:2
	ds_read2_b64 v[96:99], v110 offset0:4 offset1:6
	s_waitcnt lgkmcnt(1)
	v_mfma_f32_32x32x16_bf16 v[80:95], v[100:103], v[104:107], v[80:95]
	ds_read2_b64 v[104:107], v111 offset0:64 offset1:66
	v_readlane_b32 s20, v253, 21
	v_readlane_b32 s21, v253, 22
	s_nop 1
	v_cndmask_b32_e64 v112, 0, 1, s[20:21]
	v_readlane_b32 s20, v253, 23
	s_waitcnt lgkmcnt(0)
	v_mfma_f32_32x32x16_bf16 v[64:79], v[100:103], v[104:107], v[64:79]
	ds_read_b128 v[104:107], v214 offset:64
	ds_read_b128 v[100:103], v214 offset:96
	v_readlane_b32 s21, v253, 24
	s_waitcnt lgkmcnt(1)
	v_sub_f32_e32 v104, v206, v104
	v_cndmask_b32_e64 v113, 0, 1, s[20:21]
	v_cndmask_b32_e64 v112, v113, v112, s[14:15]
	v_readlane_b32 s20, v253, 25
	v_and_b32_e32 v112, 1, v112
	v_readlane_b32 s21, v253, 26
	v_cmp_eq_u32_e32 vcc, 1, v112
	v_mul_f32_e32 v104, 0x3fb8aa3b, v104
	v_cndmask_b32_e64 v112, 0, 1, s[20:21]
	v_readlane_b32 s20, v253, 27
	v_readlane_b32 s21, v253, 28
	v_cndmask_b32_e32 v104, v232, v104, vcc
	v_sub_f32_e32 v105, v206, v105
	v_cndmask_b32_e64 v113, 0, 1, s[20:21]
	v_cndmask_b32_e64 v112, v113, v112, s[14:15]
	v_readlane_b32 s20, v253, 29
	v_and_b32_e32 v112, 1, v112
	v_readlane_b32 s21, v253, 30
	v_cmp_eq_u32_e32 vcc, 1, v112
	v_mul_f32_e32 v105, 0x3fb8aa3b, v105
	v_cndmask_b32_e64 v112, 0, 1, s[20:21]
	v_readlane_b32 s20, v253, 31
	v_readlane_b32 s21, v253, 32
	v_cndmask_b32_e32 v105, v232, v105, vcc
	v_sub_f32_e32 v106, v206, v106
	v_cndmask_b32_e64 v113, 0, 1, s[20:21]
	v_cndmask_b32_e64 v112, v113, v112, s[14:15]
	v_readlane_b32 s20, v253, 33
	v_and_b32_e32 v112, 1, v112
	v_readlane_b32 s21, v253, 34
	v_cmp_eq_u32_e32 vcc, 1, v112
	v_mul_f32_e32 v106, 0x3fb8aa3b, v106
	v_cndmask_b32_e64 v112, 0, 1, s[20:21]
	v_readlane_b32 s20, v253, 35
	v_readlane_b32 s21, v253, 36
	v_cndmask_b32_e32 v106, v232, v106, vcc
	v_sub_f32_e32 v107, v206, v107
	v_cndmask_b32_e64 v113, 0, 1, s[20:21]
	v_cndmask_b32_e64 v112, v113, v112, s[14:15]
	v_readlane_b32 s20, v253, 37
	v_and_b32_e32 v112, 1, v112
	v_readlane_b32 s21, v253, 38
	v_cmp_eq_u32_e32 vcc, 1, v112
	v_mul_f32_e32 v107, 0x3fb8aa3b, v107
	v_cndmask_b32_e64 v112, 0, 1, s[20:21]
	v_readlane_b32 s20, v253, 39
	v_readlane_b32 s21, v253, 40
	v_cndmask_b32_e32 v107, v232, v107, vcc
	s_waitcnt lgkmcnt(0)
	v_sub_f32_e32 v100, v206, v100
	v_cndmask_b32_e64 v113, 0, 1, s[20:21]
	v_cndmask_b32_e64 v112, v113, v112, s[14:15]
	v_readlane_b32 s20, v253, 41
	v_and_b32_e32 v112, 1, v112
	v_readlane_b32 s21, v253, 42
	v_cmp_eq_u32_e32 vcc, 1, v112
	v_mul_f32_e32 v100, 0x3fb8aa3b, v100
	v_cndmask_b32_e64 v112, 0, 1, s[20:21]
	v_readlane_b32 s20, v253, 43
	v_readlane_b32 s21, v253, 44
	v_sub_f32_e32 v101, v206, v101
	v_cndmask_b32_e32 v100, v232, v100, vcc
	v_cndmask_b32_e64 v113, 0, 1, s[20:21]
	v_cndmask_b32_e64 v112, v113, v112, s[14:15]
	v_and_b32_e32 v112, 1, v112
	v_cmp_eq_u32_e32 vcc, 1, v112
	v_mul_f32_e32 v101, 0x3fb8aa3b, v101
	v_exp_f32_e32 v100, v100
	v_cndmask_b32_e32 v101, v232, v101, vcc
	v_exp_f32_e32 v101, v101
	v_readlane_b32 s20, v253, 45
	v_readlane_b32 s21, v253, 46
	v_exp_f32_e32 v104, v104
	v_pk_mul_f32 v[112:113], v[12:13], v[100:101]
	v_cndmask_b32_e64 v100, 0, 1, s[20:21]
	v_readlane_b32 s20, v253, 47
	v_readlane_b32 s21, v253, 48
	v_exp_f32_e32 v105, v105
	v_exp_f32_e32 v106, v106
	v_cndmask_b32_e64 v101, 0, 1, s[20:21]
	v_readlane_b32 s20, v253, 49
	v_readlane_b32 s21, v253, 50
	v_cndmask_b32_e64 v100, v101, v100, s[14:15]
	v_and_b32_e32 v100, 1, v100
	v_cndmask_b32_e64 v101, 0, 1, s[20:21]
	v_readlane_b32 s20, v253, 51
	v_readlane_b32 s21, v253, 52
	v_cmp_eq_u32_e32 vcc, 1, v100
	v_sub_f32_e32 v100, v206, v102
	v_cndmask_b32_e64 v102, 0, 1, s[20:21]
	v_cndmask_b32_e64 v101, v102, v101, s[14:15]
	v_mul_f32_e32 v100, 0x3fb8aa3b, v100
	v_and_b32_e32 v101, 1, v101
	v_cndmask_b32_e32 v100, v232, v100, vcc
	v_cmp_eq_u32_e32 vcc, 1, v101
	v_sub_f32_e32 v101, v206, v103
	v_mul_f32_e32 v101, 0x3fb8aa3b, v101
	v_cndmask_b32_e32 v101, v232, v101, vcc
	v_exp_f32_e32 v107, v107
	v_exp_f32_e32 v100, v100
	v_exp_f32_e32 v101, v101
	v_pk_mul_f32 v[104:105], v[8:9], v[104:105]
	v_pk_mul_f32 v[106:107], v[10:11], v[106:107]
	v_cvt_pk_bf16_f32 v102, v112, v113
	v_pk_mul_f32 v[114:115], v[14:15], v[100:101]
	v_cvt_pk_bf16_f32 v100, v104, v105
	v_cvt_pk_bf16_f32 v101, v106, v107
	v_cvt_pk_bf16_f32 v103, v114, v115
	s_nop 1
	v_mfma_f32_32x32x16_bf16 v[80:95], v[100:103], v[96:99], v[80:95]
	ds_read2_b64 v[96:99], v111 offset0:68 offset1:70
	s_waitcnt lgkmcnt(0)
	v_mfma_f32_32x32x16_bf16 v[64:79], v[100:103], v[96:99], v[64:79]
.LBB0_2107:
	s_or_b64 exec, exec, s[16:17]
	v_cndmask_b32_e64 v96, 0, 1, s[74:75]
	v_cndmask_b32_e64 v97, 0, 1, s[76:77]
	v_cndmask_b32_e64 v96, v97, v96, s[14:15]
	v_and_b32_e32 v96, 1, v96
	v_cmp_eq_u32_e32 vcc, 1, v96
	s_and_saveexec_b64 s[16:17], vcc
	s_cbranch_execz .LBB0_2109
	ds_read_b128 v[100:103], v214 offset:128
	ds_read_b128 v[96:99], v214 offset:160
	v_readlane_b32 s20, v253, 53
	v_readlane_b32 s21, v253, 54
	v_add_u32_e32 v111, 0x2000, v110
	s_waitcnt lgkmcnt(1)
	v_sub_f32_e32 v100, v206, v100
	v_cndmask_b32_e64 v104, 0, 1, s[20:21]
	v_readlane_b32 s20, v253, 55
	v_readlane_b32 s21, v253, 56
	v_mul_f32_e32 v100, 0x3fb8aa3b, v100
	v_sub_f32_e32 v101, v206, v101
	v_cndmask_b32_e64 v105, 0, 1, s[20:21]
	v_cndmask_b32_e64 v104, v105, v104, s[14:15]
	v_readlane_b32 s20, v253, 57
	v_and_b32_e32 v104, 1, v104
	v_readlane_b32 s21, v253, 58
	v_cmp_eq_u32_e32 vcc, 1, v104
	v_mul_f32_e32 v101, 0x3fb8aa3b, v101
	v_cndmask_b32_e64 v104, 0, 1, s[20:21]
	v_readlane_b32 s20, v253, 59
	v_readlane_b32 s21, v253, 60
	v_cndmask_b32_e32 v100, v232, v100, vcc
	v_sub_f32_e32 v102, v206, v102
	v_cndmask_b32_e64 v105, 0, 1, s[20:21]
	v_cndmask_b32_e64 v104, v105, v104, s[14:15]
	v_readlane_b32 s20, v253, 61
	v_and_b32_e32 v104, 1, v104
	v_readlane_b32 s21, v253, 62
	v_cmp_eq_u32_e32 vcc, 1, v104
	v_mul_f32_e32 v102, 0x3fb8aa3b, v102
	v_cndmask_b32_e64 v104, 0, 1, s[20:21]
	v_readlane_b32 s20, v253, 63
	v_readlane_b32 s21, v254, 0
	v_cndmask_b32_e32 v101, v232, v101, vcc
	v_sub_f32_e32 v103, v206, v103
	v_cndmask_b32_e64 v105, 0, 1, s[20:21]
	v_cndmask_b32_e64 v104, v105, v104, s[14:15]
	v_readlane_b32 s20, v254, 1
	v_and_b32_e32 v104, 1, v104
	v_readlane_b32 s21, v254, 2
	v_cmp_eq_u32_e32 vcc, 1, v104
	v_mul_f32_e32 v103, 0x3fb8aa3b, v103
	v_cndmask_b32_e64 v104, 0, 1, s[20:21]
	v_readlane_b32 s20, v254, 3
	v_readlane_b32 s21, v254, 4
	v_cndmask_b32_e32 v102, v232, v102, vcc
	s_waitcnt lgkmcnt(0)
	v_sub_f32_e32 v96, v206, v96
	v_cndmask_b32_e64 v105, 0, 1, s[20:21]
	v_cndmask_b32_e64 v104, v105, v104, s[14:15]
	v_readlane_b32 s20, v254, 5
	v_and_b32_e32 v104, 1, v104
	v_readlane_b32 s21, v254, 6
	v_cmp_eq_u32_e32 vcc, 1, v104
	v_mul_f32_e32 v96, 0x3fb8aa3b, v96
	v_cndmask_b32_e64 v104, 0, 1, s[20:21]
	v_readlane_b32 s20, v254, 7
	v_readlane_b32 s21, v254, 8
	v_cndmask_b32_e32 v103, v232, v103, vcc
	v_sub_f32_e32 v97, v206, v97
	v_cndmask_b32_e64 v105, 0, 1, s[20:21]
	v_cndmask_b32_e64 v104, v105, v104, s[14:15]
	v_readlane_b32 s20, v254, 9
	v_and_b32_e32 v104, 1, v104
	v_readlane_b32 s21, v254, 10
	v_cmp_eq_u32_e32 vcc, 1, v104
	v_mul_f32_e32 v97, 0x3fb8aa3b, v97
	v_cndmask_b32_e64 v104, 0, 1, s[20:21]
	v_readlane_b32 s20, v254, 11
	v_readlane_b32 s21, v254, 12
	v_cndmask_b32_e32 v96, v232, v96, vcc
	v_sub_f32_e32 v98, v206, v98
	v_cndmask_b32_e64 v105, 0, 1, s[20:21]
	v_cndmask_b32_e64 v104, v105, v104, s[14:15]
	v_readlane_b32 s20, v254, 13
	v_and_b32_e32 v104, 1, v104
	v_readlane_b32 s21, v254, 14
	v_cmp_eq_u32_e32 vcc, 1, v104
	v_mul_f32_e32 v98, 0x3fb8aa3b, v98
	v_cndmask_b32_e64 v104, 0, 1, s[20:21]
	v_readlane_b32 s20, v254, 15
	v_readlane_b32 s21, v254, 16
	v_cndmask_b32_e32 v97, v232, v97, vcc
	v_sub_f32_e32 v99, v206, v99
	v_cndmask_b32_e64 v105, 0, 1, s[20:21]
	v_cndmask_b32_e64 v104, v105, v104, s[14:15]
	v_readlane_b32 s20, v254, 17
	v_and_b32_e32 v104, 1, v104
	v_readlane_b32 s21, v254, 18
	v_cmp_eq_u32_e32 vcc, 1, v104
	v_mul_f32_e32 v99, 0x3fb8aa3b, v99
	v_cndmask_b32_e64 v104, 0, 1, s[20:21]
	v_readlane_b32 s20, v254, 19
	v_readlane_b32 s21, v254, 20
	v_cndmask_b32_e32 v98, v232, v98, vcc
	v_exp_f32_e32 v100, v100
	v_cndmask_b32_e64 v105, 0, 1, s[20:21]
	v_cndmask_b32_e64 v104, v105, v104, s[14:15]
	v_and_b32_e32 v104, 1, v104
	v_cmp_eq_u32_e32 vcc, 1, v104
	v_exp_f32_e32 v101, v101
	v_exp_f32_e32 v102, v102
	v_cndmask_b32_e32 v99, v232, v99, vcc
	v_exp_f32_e32 v103, v103
	v_exp_f32_e32 v96, v96
	v_exp_f32_e32 v97, v97
	v_exp_f32_e32 v98, v98
	v_exp_f32_e32 v99, v99
	v_pk_mul_f32 v[100:101], v[16:17], v[100:101]
	v_pk_mul_f32 v[102:103], v[18:19], v[102:103]
	v_pk_mul_f32 v[96:97], v[20:21], v[96:97]
	v_pk_mul_f32 v[98:99], v[22:23], v[98:99]
	v_cvt_pk_bf16_f32 v100, v100, v101
	v_cvt_pk_bf16_f32 v101, v102, v103
	v_cvt_pk_bf16_f32 v102, v96, v97
	v_cvt_pk_bf16_f32 v103, v98, v99
	ds_read2_b64 v[104:107], v110 offset0:8 offset1:10
	ds_read2_b64 v[96:99], v110 offset0:12 offset1:14
	s_waitcnt lgkmcnt(1)
	v_mfma_f32_32x32x16_bf16 v[80:95], v[100:103], v[104:107], v[80:95]
	ds_read2_b64 v[104:107], v111 offset0:72 offset1:74
	v_readlane_b32 s20, v254, 21
	v_readlane_b32 s21, v254, 22
	s_nop 1
	v_cndmask_b32_e64 v112, 0, 1, s[20:21]
	v_readlane_b32 s20, v254, 23
	s_waitcnt lgkmcnt(0)
	v_mfma_f32_32x32x16_bf16 v[64:79], v[100:103], v[104:107], v[64:79]
	ds_read_b128 v[104:107], v214 offset:192
	ds_read_b128 v[100:103], v214 offset:224
	v_readlane_b32 s21, v254, 24
	s_waitcnt lgkmcnt(1)
	v_sub_f32_e32 v104, v206, v104
	v_cndmask_b32_e64 v113, 0, 1, s[20:21]
	v_cndmask_b32_e64 v112, v113, v112, s[14:15]
	v_readlane_b32 s20, v254, 25
	v_and_b32_e32 v112, 1, v112
	v_readlane_b32 s21, v254, 26
	v_cmp_eq_u32_e32 vcc, 1, v112
	v_mul_f32_e32 v104, 0x3fb8aa3b, v104
	v_cndmask_b32_e64 v112, 0, 1, s[20:21]
	v_readlane_b32 s20, v254, 27
	v_readlane_b32 s21, v254, 28
	v_cndmask_b32_e32 v104, v232, v104, vcc
	v_sub_f32_e32 v105, v206, v105
	v_cndmask_b32_e64 v113, 0, 1, s[20:21]
	v_cndmask_b32_e64 v112, v113, v112, s[14:15]
	v_readlane_b32 s20, v254, 29
	v_and_b32_e32 v112, 1, v112
	v_readlane_b32 s21, v254, 30
	v_cmp_eq_u32_e32 vcc, 1, v112
	v_mul_f32_e32 v105, 0x3fb8aa3b, v105
	v_cndmask_b32_e64 v112, 0, 1, s[20:21]
	v_readlane_b32 s20, v254, 31
	v_readlane_b32 s21, v254, 32
	v_cndmask_b32_e32 v105, v232, v105, vcc
	v_sub_f32_e32 v106, v206, v106
	v_cndmask_b32_e64 v113, 0, 1, s[20:21]
	v_cndmask_b32_e64 v112, v113, v112, s[14:15]
	v_readlane_b32 s20, v254, 33
	v_and_b32_e32 v112, 1, v112
	v_readlane_b32 s21, v254, 34
	v_cmp_eq_u32_e32 vcc, 1, v112
	v_mul_f32_e32 v106, 0x3fb8aa3b, v106
	v_cndmask_b32_e64 v112, 0, 1, s[20:21]
	v_readlane_b32 s20, v254, 35
	v_readlane_b32 s21, v254, 36
	v_cndmask_b32_e32 v106, v232, v106, vcc
	v_sub_f32_e32 v107, v206, v107
	v_cndmask_b32_e64 v113, 0, 1, s[20:21]
	v_cndmask_b32_e64 v112, v113, v112, s[14:15]
	v_readlane_b32 s20, v254, 37
	v_and_b32_e32 v112, 1, v112
	v_readlane_b32 s21, v254, 38
	v_cmp_eq_u32_e32 vcc, 1, v112
	v_mul_f32_e32 v107, 0x3fb8aa3b, v107
	v_cndmask_b32_e64 v112, 0, 1, s[20:21]
	v_readlane_b32 s20, v254, 39
	v_readlane_b32 s21, v254, 40
	v_cndmask_b32_e32 v107, v232, v107, vcc
	s_waitcnt lgkmcnt(0)
	v_sub_f32_e32 v100, v206, v100
	v_cndmask_b32_e64 v113, 0, 1, s[20:21]
	v_cndmask_b32_e64 v112, v113, v112, s[14:15]
	v_readlane_b32 s20, v254, 41
	v_and_b32_e32 v112, 1, v112
	v_readlane_b32 s21, v254, 42
	v_cmp_eq_u32_e32 vcc, 1, v112
	v_mul_f32_e32 v100, 0x3fb8aa3b, v100
	v_cndmask_b32_e64 v112, 0, 1, s[20:21]
	v_readlane_b32 s20, v254, 43
	v_readlane_b32 s21, v254, 44
	v_sub_f32_e32 v101, v206, v101
	v_cndmask_b32_e32 v100, v232, v100, vcc
	v_cndmask_b32_e64 v113, 0, 1, s[20:21]
	v_cndmask_b32_e64 v112, v113, v112, s[14:15]
	v_and_b32_e32 v112, 1, v112
	v_cmp_eq_u32_e32 vcc, 1, v112
	v_mul_f32_e32 v101, 0x3fb8aa3b, v101
	v_exp_f32_e32 v100, v100
	v_cndmask_b32_e32 v101, v232, v101, vcc
	v_exp_f32_e32 v101, v101
	v_readlane_b32 s20, v254, 45
	v_readlane_b32 s21, v254, 46
	v_exp_f32_e32 v104, v104
	v_pk_mul_f32 v[112:113], v[28:29], v[100:101]
	v_cndmask_b32_e64 v100, 0, 1, s[20:21]
	v_readlane_b32 s20, v254, 47
	v_readlane_b32 s21, v254, 48
	v_exp_f32_e32 v105, v105
	v_exp_f32_e32 v106, v106
	v_cndmask_b32_e64 v101, 0, 1, s[20:21]
	v_readlane_b32 s20, v254, 49
	v_readlane_b32 s21, v254, 50
	v_cndmask_b32_e64 v100, v101, v100, s[14:15]
	v_and_b32_e32 v100, 1, v100
	v_cndmask_b32_e64 v101, 0, 1, s[20:21]
	v_readlane_b32 s20, v254, 51
	v_readlane_b32 s21, v254, 52
	v_cmp_eq_u32_e32 vcc, 1, v100
	v_sub_f32_e32 v100, v206, v102
	v_cndmask_b32_e64 v102, 0, 1, s[20:21]
	v_cndmask_b32_e64 v101, v102, v101, s[14:15]
	v_mul_f32_e32 v100, 0x3fb8aa3b, v100
	v_and_b32_e32 v101, 1, v101
	v_cndmask_b32_e32 v100, v232, v100, vcc
	v_cmp_eq_u32_e32 vcc, 1, v101
	v_sub_f32_e32 v101, v206, v103
	v_mul_f32_e32 v101, 0x3fb8aa3b, v101
	v_cndmask_b32_e32 v101, v232, v101, vcc
	v_exp_f32_e32 v107, v107
	v_exp_f32_e32 v100, v100
	v_exp_f32_e32 v101, v101
	v_pk_mul_f32 v[104:105], v[24:25], v[104:105]
	v_pk_mul_f32 v[106:107], v[26:27], v[106:107]
	v_cvt_pk_bf16_f32 v102, v112, v113
	v_pk_mul_f32 v[114:115], v[30:31], v[100:101]
	v_cvt_pk_bf16_f32 v100, v104, v105
	v_cvt_pk_bf16_f32 v101, v106, v107
	v_cvt_pk_bf16_f32 v103, v114, v115
	s_nop 1
	v_mfma_f32_32x32x16_bf16 v[80:95], v[100:103], v[96:99], v[80:95]
	ds_read2_b64 v[96:99], v111 offset0:76 offset1:78
	s_waitcnt lgkmcnt(0)
	v_mfma_f32_32x32x16_bf16 v[64:79], v[100:103], v[96:99], v[64:79]
.LBB0_2109:
	s_or_b64 exec, exec, s[16:17]
	v_cndmask_b32_e64 v96, 0, 1, s[50:51]
	v_cndmask_b32_e64 v97, 0, 1, s[52:53]
	v_cndmask_b32_e64 v96, v97, v96, s[14:15]
	v_and_b32_e32 v96, 1, v96
	v_cmp_eq_u32_e32 vcc, 1, v96
	s_and_saveexec_b64 s[16:17], vcc
	s_cbranch_execz .LBB0_2111
	ds_read_b128 v[100:103], v214 offset:256
	ds_read_b128 v[96:99], v214 offset:288
	v_readlane_b32 s20, v254, 53
	v_readlane_b32 s21, v254, 54
	v_add_u32_e32 v111, 0x2000, v110
	s_waitcnt lgkmcnt(1)
	v_sub_f32_e32 v100, v206, v100
	v_cndmask_b32_e64 v104, 0, 1, s[20:21]
	v_readlane_b32 s20, v254, 55
	v_readlane_b32 s21, v254, 56
	v_mul_f32_e32 v100, 0x3fb8aa3b, v100
	v_sub_f32_e32 v101, v206, v101
	v_cndmask_b32_e64 v105, 0, 1, s[20:21]
	v_cndmask_b32_e64 v104, v105, v104, s[14:15]
	v_readlane_b32 s20, v254, 57
	v_and_b32_e32 v104, 1, v104
	v_readlane_b32 s21, v254, 58
	v_cmp_eq_u32_e32 vcc, 1, v104
	v_mul_f32_e32 v101, 0x3fb8aa3b, v101
	v_cndmask_b32_e64 v104, 0, 1, s[20:21]
	v_readlane_b32 s20, v254, 59
	v_readlane_b32 s21, v254, 60
	v_cndmask_b32_e32 v100, v232, v100, vcc
	v_sub_f32_e32 v102, v206, v102
	v_cndmask_b32_e64 v105, 0, 1, s[20:21]
	v_cndmask_b32_e64 v104, v105, v104, s[14:15]
	v_readlane_b32 s20, v254, 61
	v_and_b32_e32 v104, 1, v104
	v_readlane_b32 s21, v254, 62
	v_cmp_eq_u32_e32 vcc, 1, v104
	v_mul_f32_e32 v102, 0x3fb8aa3b, v102
	v_cndmask_b32_e64 v104, 0, 1, s[20:21]
	v_readlane_b32 s20, v254, 63
	v_readlane_b32 s21, v255, 0
	v_cndmask_b32_e32 v101, v232, v101, vcc
	v_sub_f32_e32 v103, v206, v103
	v_cndmask_b32_e64 v105, 0, 1, s[20:21]
	v_cndmask_b32_e64 v104, v105, v104, s[14:15]
	v_readlane_b32 s20, v255, 1
	v_and_b32_e32 v104, 1, v104
	v_readlane_b32 s21, v255, 2
	v_cmp_eq_u32_e32 vcc, 1, v104
	v_mul_f32_e32 v103, 0x3fb8aa3b, v103
	v_cndmask_b32_e64 v104, 0, 1, s[20:21]
	v_readlane_b32 s20, v255, 3
	v_readlane_b32 s21, v255, 4
	v_cndmask_b32_e32 v102, v232, v102, vcc
	s_waitcnt lgkmcnt(0)
	v_sub_f32_e32 v96, v206, v96
	v_cndmask_b32_e64 v105, 0, 1, s[20:21]
	v_cndmask_b32_e64 v104, v105, v104, s[14:15]
	v_readlane_b32 s20, v255, 5
	v_and_b32_e32 v104, 1, v104
	v_readlane_b32 s21, v255, 6
	v_cmp_eq_u32_e32 vcc, 1, v104
	v_mul_f32_e32 v96, 0x3fb8aa3b, v96
	v_cndmask_b32_e64 v104, 0, 1, s[20:21]
	v_readlane_b32 s20, v255, 7
	v_readlane_b32 s21, v255, 8
	v_cndmask_b32_e32 v103, v232, v103, vcc
	v_sub_f32_e32 v97, v206, v97
	v_cndmask_b32_e64 v105, 0, 1, s[20:21]
	v_cndmask_b32_e64 v104, v105, v104, s[14:15]
	v_readlane_b32 s20, v255, 9
	v_and_b32_e32 v104, 1, v104
	v_readlane_b32 s21, v255, 10
	v_cmp_eq_u32_e32 vcc, 1, v104
	v_mul_f32_e32 v97, 0x3fb8aa3b, v97
	v_cndmask_b32_e64 v104, 0, 1, s[20:21]
	v_readlane_b32 s20, v255, 11
	v_readlane_b32 s21, v255, 12
	v_cndmask_b32_e32 v96, v232, v96, vcc
	v_sub_f32_e32 v98, v206, v98
	v_cndmask_b32_e64 v105, 0, 1, s[20:21]
	v_cndmask_b32_e64 v104, v105, v104, s[14:15]
	v_readlane_b32 s20, v255, 13
	v_and_b32_e32 v104, 1, v104
	v_readlane_b32 s21, v255, 14
	v_cmp_eq_u32_e32 vcc, 1, v104
	v_mul_f32_e32 v98, 0x3fb8aa3b, v98
	v_cndmask_b32_e64 v104, 0, 1, s[20:21]
	v_readlane_b32 s20, v255, 15
	v_readlane_b32 s21, v255, 16
	v_cndmask_b32_e32 v97, v232, v97, vcc
	v_sub_f32_e32 v99, v206, v99
	v_cndmask_b32_e64 v105, 0, 1, s[20:21]
	v_cndmask_b32_e64 v104, v105, v104, s[14:15]
	v_readlane_b32 s20, v255, 17
	v_and_b32_e32 v104, 1, v104
	v_readlane_b32 s21, v255, 18
	v_cmp_eq_u32_e32 vcc, 1, v104
	v_mul_f32_e32 v99, 0x3fb8aa3b, v99
	v_cndmask_b32_e64 v104, 0, 1, s[20:21]
	v_readlane_b32 s20, v255, 19
	v_readlane_b32 s21, v255, 20
	v_cndmask_b32_e32 v98, v232, v98, vcc
	v_exp_f32_e32 v100, v100
	v_cndmask_b32_e64 v105, 0, 1, s[20:21]
	v_cndmask_b32_e64 v104, v105, v104, s[14:15]
	v_and_b32_e32 v104, 1, v104
	v_cmp_eq_u32_e32 vcc, 1, v104
	v_exp_f32_e32 v101, v101
	v_exp_f32_e32 v102, v102
	v_cndmask_b32_e32 v99, v232, v99, vcc
	v_exp_f32_e32 v103, v103
	v_exp_f32_e32 v96, v96
	v_exp_f32_e32 v97, v97
	v_exp_f32_e32 v98, v98
	v_exp_f32_e32 v99, v99
	v_pk_mul_f32 v[100:101], v[32:33], v[100:101]
	v_pk_mul_f32 v[102:103], v[34:35], v[102:103]
	v_pk_mul_f32 v[96:97], v[36:37], v[96:97]
	v_pk_mul_f32 v[98:99], v[38:39], v[98:99]
	v_cvt_pk_bf16_f32 v100, v100, v101
	v_cvt_pk_bf16_f32 v101, v102, v103
	v_cvt_pk_bf16_f32 v102, v96, v97
	v_cvt_pk_bf16_f32 v103, v98, v99
	ds_read2_b64 v[104:107], v110 offset0:16 offset1:18
	ds_read2_b64 v[96:99], v110 offset0:20 offset1:22
	s_waitcnt lgkmcnt(1)
	v_mfma_f32_32x32x16_bf16 v[80:95], v[100:103], v[104:107], v[80:95]
	ds_read2_b64 v[104:107], v111 offset0:80 offset1:82
	v_readlane_b32 s20, v255, 21
	v_readlane_b32 s21, v255, 22
	s_nop 1
	v_cndmask_b32_e64 v112, 0, 1, s[20:21]
	v_readlane_b32 s20, v255, 23
	s_waitcnt lgkmcnt(0)
	v_mfma_f32_32x32x16_bf16 v[64:79], v[100:103], v[104:107], v[64:79]
	ds_read_b128 v[104:107], v214 offset:320
	ds_read_b128 v[100:103], v214 offset:352
	v_readlane_b32 s21, v255, 24
	s_waitcnt lgkmcnt(1)
	v_sub_f32_e32 v104, v206, v104
	v_cndmask_b32_e64 v113, 0, 1, s[20:21]
	v_cndmask_b32_e64 v112, v113, v112, s[14:15]
	v_readlane_b32 s20, v255, 25
	v_and_b32_e32 v112, 1, v112
	v_readlane_b32 s21, v255, 26
	v_cmp_eq_u32_e32 vcc, 1, v112
	v_mul_f32_e32 v104, 0x3fb8aa3b, v104
	v_cndmask_b32_e64 v112, 0, 1, s[20:21]
	v_readlane_b32 s20, v255, 27
	v_readlane_b32 s21, v255, 28
	v_cndmask_b32_e32 v104, v232, v104, vcc
	v_sub_f32_e32 v105, v206, v105
	v_cndmask_b32_e64 v113, 0, 1, s[20:21]
	v_cndmask_b32_e64 v112, v113, v112, s[14:15]
	v_readlane_b32 s20, v255, 29
	v_and_b32_e32 v112, 1, v112
	v_readlane_b32 s21, v255, 30
	v_cmp_eq_u32_e32 vcc, 1, v112
	v_mul_f32_e32 v105, 0x3fb8aa3b, v105
	v_cndmask_b32_e64 v112, 0, 1, s[20:21]
	v_readlane_b32 s20, v255, 31
	v_readlane_b32 s21, v255, 32
	v_cndmask_b32_e32 v105, v232, v105, vcc
	v_sub_f32_e32 v106, v206, v106
	v_cndmask_b32_e64 v113, 0, 1, s[20:21]
	v_cndmask_b32_e64 v112, v113, v112, s[14:15]
	v_readlane_b32 s20, v255, 33
	v_and_b32_e32 v112, 1, v112
	v_readlane_b32 s21, v255, 34
	v_cmp_eq_u32_e32 vcc, 1, v112
	v_mul_f32_e32 v106, 0x3fb8aa3b, v106
	v_cndmask_b32_e64 v112, 0, 1, s[20:21]
	v_readlane_b32 s20, v255, 35
	v_readlane_b32 s21, v255, 36
	v_cndmask_b32_e32 v106, v232, v106, vcc
	v_sub_f32_e32 v107, v206, v107
	v_cndmask_b32_e64 v113, 0, 1, s[20:21]
	v_cndmask_b32_e64 v112, v113, v112, s[14:15]
	v_readlane_b32 s20, v255, 37
	v_and_b32_e32 v112, 1, v112
	v_readlane_b32 s21, v255, 38
	v_cmp_eq_u32_e32 vcc, 1, v112
	v_mul_f32_e32 v107, 0x3fb8aa3b, v107
	v_cndmask_b32_e64 v112, 0, 1, s[20:21]
	v_readlane_b32 s20, v255, 39
	v_readlane_b32 s21, v255, 40
	v_cndmask_b32_e32 v107, v232, v107, vcc
	s_waitcnt lgkmcnt(0)
	v_sub_f32_e32 v100, v206, v100
	v_cndmask_b32_e64 v113, 0, 1, s[20:21]
	v_cndmask_b32_e64 v112, v113, v112, s[14:15]
	v_readlane_b32 s20, v255, 41
	v_and_b32_e32 v112, 1, v112
	v_readlane_b32 s21, v255, 42
	v_cmp_eq_u32_e32 vcc, 1, v112
	v_mul_f32_e32 v100, 0x3fb8aa3b, v100
	v_cndmask_b32_e64 v112, 0, 1, s[20:21]
	v_readlane_b32 s20, v255, 43
	v_readlane_b32 s21, v255, 44
	v_sub_f32_e32 v101, v206, v101
	v_cndmask_b32_e32 v100, v232, v100, vcc
	v_cndmask_b32_e64 v113, 0, 1, s[20:21]
	v_cndmask_b32_e64 v112, v113, v112, s[14:15]
	v_and_b32_e32 v112, 1, v112
	v_cmp_eq_u32_e32 vcc, 1, v112
	v_mul_f32_e32 v101, 0x3fb8aa3b, v101
	v_exp_f32_e32 v100, v100
	v_cndmask_b32_e32 v101, v232, v101, vcc
	v_exp_f32_e32 v101, v101
	v_readlane_b32 s20, v255, 45
	v_readlane_b32 s21, v255, 46
	v_exp_f32_e32 v104, v104
	v_pk_mul_f32 v[112:113], v[44:45], v[100:101]
	v_cndmask_b32_e64 v100, 0, 1, s[20:21]
	v_readlane_b32 s20, v255, 47
	v_readlane_b32 s21, v255, 48
	v_exp_f32_e32 v105, v105
	v_exp_f32_e32 v106, v106
	v_cndmask_b32_e64 v101, 0, 1, s[20:21]
	v_cndmask_b32_e64 v100, v101, v100, s[14:15]
	v_and_b32_e32 v100, 1, v100
	v_cmp_eq_u32_e32 vcc, 1, v100
	v_sub_f32_e32 v100, v206, v102
	v_cndmask_b32_e64 v101, 0, 1, s[24:25]
	v_cndmask_b32_e64 v102, 0, 1, s[26:27]
	v_cndmask_b32_e64 v101, v102, v101, s[14:15]
	v_mul_f32_e32 v100, 0x3fb8aa3b, v100
	v_and_b32_e32 v101, 1, v101
	v_cndmask_b32_e32 v100, v232, v100, vcc
	v_cmp_eq_u32_e32 vcc, 1, v101
	v_sub_f32_e32 v101, v206, v103
	v_mul_f32_e32 v101, 0x3fb8aa3b, v101
	v_cndmask_b32_e32 v101, v232, v101, vcc
	v_exp_f32_e32 v107, v107
	v_exp_f32_e32 v100, v100
	v_exp_f32_e32 v101, v101
	v_pk_mul_f32 v[104:105], v[40:41], v[104:105]
	v_pk_mul_f32 v[106:107], v[42:43], v[106:107]
	v_cvt_pk_bf16_f32 v102, v112, v113
	v_pk_mul_f32 v[114:115], v[46:47], v[100:101]
	v_cvt_pk_bf16_f32 v100, v104, v105
	v_cvt_pk_bf16_f32 v101, v106, v107
	v_cvt_pk_bf16_f32 v103, v114, v115
	s_nop 1
	v_mfma_f32_32x32x16_bf16 v[80:95], v[100:103], v[96:99], v[80:95]
	ds_read2_b64 v[96:99], v111 offset0:84 offset1:86
	s_waitcnt lgkmcnt(0)
	v_mfma_f32_32x32x16_bf16 v[64:79], v[100:103], v[96:99], v[64:79]
.LBB0_2111:
	s_or_b64 exec, exec, s[16:17]
	v_cndmask_b32_e64 v96, 0, 1, s[28:29]
	v_cndmask_b32_e64 v97, 0, 1, s[30:31]
	v_cndmask_b32_e64 v96, v97, v96, s[14:15]
	v_and_b32_e32 v96, 1, v96
	v_cmp_eq_u32_e32 vcc, 1, v96
	s_and_saveexec_b64 s[16:17], vcc
	s_cbranch_execz .LBB0_2104
	ds_read_b128 v[100:103], v214 offset:384
	ds_read_b128 v[96:99], v214 offset:416
	v_cndmask_b32_e64 v104, 0, 1, s[34:35]
	v_cndmask_b32_e64 v105, 0, 1, s[36:37]
	v_cndmask_b32_e64 v104, v105, v104, s[14:15]
	v_and_b32_e32 v104, 1, v104
	v_cmp_eq_u32_e32 vcc, 1, v104
	v_cndmask_b32_e64 v104, 0, 1, s[38:39]
	v_cndmask_b32_e64 v105, 0, 1, s[40:41]
	v_cndmask_b32_e64 v104, v105, v104, s[14:15]
	v_and_b32_e32 v104, 1, v104
	v_cndmask_b32_e64 v105, 0, 1, s[44:45]
	s_waitcnt lgkmcnt(1)
	v_sub_f32_e32 v100, v206, v100
	v_mul_f32_e32 v100, 0x3fb8aa3b, v100
	v_cndmask_b32_e32 v100, v232, v100, vcc
	v_cmp_eq_u32_e32 vcc, 1, v104
	v_cndmask_b32_e64 v104, 0, 1, s[42:43]
	v_sub_f32_e32 v101, v206, v101
	v_cndmask_b32_e64 v104, v105, v104, s[14:15]
	v_mul_f32_e32 v101, 0x3fb8aa3b, v101
	v_and_b32_e32 v104, 1, v104
	v_cndmask_b32_e32 v101, v232, v101, vcc
	v_cmp_eq_u32_e32 vcc, 1, v104
	v_cndmask_b32_e64 v104, 0, 1, s[46:47]
	v_cndmask_b32_e64 v105, 0, 1, s[48:49]
	v_sub_f32_e32 v102, v206, v102
	v_cndmask_b32_e64 v104, v105, v104, s[14:15]
	v_mul_f32_e32 v102, 0x3fb8aa3b, v102
	v_and_b32_e32 v104, 1, v104
	v_cndmask_b32_e32 v102, v232, v102, vcc
	v_cmp_eq_u32_e32 vcc, 1, v104
	v_cndmask_b32_e64 v104, 0, 1, s[54:55]
	v_cndmask_b32_e64 v105, 0, 1, s[56:57]
	v_sub_f32_e32 v103, v206, v103
	v_cndmask_b32_e64 v104, v105, v104, s[14:15]
	v_mul_f32_e32 v103, 0x3fb8aa3b, v103
	v_and_b32_e32 v104, 1, v104
	v_cndmask_b32_e32 v103, v232, v103, vcc
	v_cmp_eq_u32_e32 vcc, 1, v104
	v_cndmask_b32_e64 v104, 0, 1, s[58:59]
	v_cndmask_b32_e64 v105, 0, 1, s[60:61]
	s_waitcnt lgkmcnt(0)
	v_sub_f32_e32 v96, v206, v96
	v_cndmask_b32_e64 v104, v105, v104, s[14:15]
	v_mul_f32_e32 v96, 0x3fb8aa3b, v96
	v_and_b32_e32 v104, 1, v104
	v_cndmask_b32_e32 v96, v232, v96, vcc
	v_cmp_eq_u32_e32 vcc, 1, v104
	v_cndmask_b32_e64 v104, 0, 1, s[62:63]
	v_cndmask_b32_e64 v105, 0, 1, s[64:65]
	v_sub_f32_e32 v97, v206, v97
	v_cndmask_b32_e64 v104, v105, v104, s[14:15]
	v_mul_f32_e32 v97, 0x3fb8aa3b, v97
	v_and_b32_e32 v104, 1, v104
	v_cndmask_b32_e32 v97, v232, v97, vcc
	v_cmp_eq_u32_e32 vcc, 1, v104
	v_cndmask_b32_e64 v104, 0, 1, s[66:67]
	v_cndmask_b32_e64 v105, 0, 1, s[68:69]
	v_sub_f32_e32 v98, v206, v98
	v_cndmask_b32_e64 v104, v105, v104, s[14:15]
	v_mul_f32_e32 v98, 0x3fb8aa3b, v98
	v_and_b32_e32 v104, 1, v104
	v_sub_f32_e32 v99, v206, v99
	v_cndmask_b32_e32 v98, v232, v98, vcc
	v_cmp_eq_u32_e32 vcc, 1, v104
	v_mul_f32_e32 v99, 0x3fb8aa3b, v99
	v_exp_f32_e32 v100, v100
	v_cndmask_b32_e32 v99, v232, v99, vcc
	v_exp_f32_e32 v101, v101
	v_exp_f32_e32 v102, v102
	v_exp_f32_e32 v103, v103
	v_exp_f32_e32 v96, v96
	v_exp_f32_e32 v97, v97
	v_exp_f32_e32 v98, v98
	v_exp_f32_e32 v99, v99
	v_pk_mul_f32 v[100:101], v[48:49], v[100:101]
	v_pk_mul_f32 v[102:103], v[50:51], v[102:103]
	v_pk_mul_f32 v[96:97], v[52:53], v[96:97]
	v_pk_mul_f32 v[98:99], v[54:55], v[98:99]
	v_cvt_pk_bf16_f32 v100, v100, v101
	v_cvt_pk_bf16_f32 v101, v102, v103
	v_cvt_pk_bf16_f32 v102, v96, v97
	v_cvt_pk_bf16_f32 v103, v98, v99
	ds_read2_b64 v[104:107], v110 offset0:24 offset1:26
	ds_read2_b64 v[96:99], v110 offset0:28 offset1:30
	v_add_u32_e32 v110, 0x2000, v110
	s_waitcnt lgkmcnt(1)
	v_mfma_f32_32x32x16_bf16 v[80:95], v[100:103], v[104:107], v[80:95]
	ds_read2_b64 v[104:107], v110 offset0:88 offset1:90
	s_waitcnt lgkmcnt(0)
	v_mfma_f32_32x32x16_bf16 v[64:79], v[100:103], v[104:107], v[64:79]
	ds_read_b128 v[104:107], v214 offset:448
	ds_read_b128 v[100:103], v214 offset:480
	v_cndmask_b32_e64 v108, 0, 1, s[70:71]
	v_cndmask_b32_e64 v109, 0, 1, s[72:73]
	v_cndmask_b32_e64 v108, v109, v108, s[14:15]
	v_and_b32_e32 v108, 1, v108
	v_cmp_eq_u32_e32 vcc, 1, v108
	v_cndmask_b32_e64 v108, 0, 1, s[78:79]
	v_cndmask_b32_e64 v109, 0, 1, s[80:81]
	v_cndmask_b32_e64 v108, v109, v108, s[14:15]
	v_and_b32_e32 v108, 1, v108
	v_cndmask_b32_e64 v109, 0, 1, s[84:85]
	s_waitcnt lgkmcnt(1)
	v_sub_f32_e32 v104, v206, v104
	v_mul_f32_e32 v104, 0x3fb8aa3b, v104
	v_cndmask_b32_e32 v104, v232, v104, vcc
	v_cmp_eq_u32_e32 vcc, 1, v108
	v_cndmask_b32_e64 v108, 0, 1, s[82:83]
	v_sub_f32_e32 v105, v206, v105
	v_cndmask_b32_e64 v108, v109, v108, s[14:15]
	v_mul_f32_e32 v105, 0x3fb8aa3b, v105
	v_and_b32_e32 v108, 1, v108
	v_cndmask_b32_e32 v105, v232, v105, vcc
	v_cmp_eq_u32_e32 vcc, 1, v108
	v_cndmask_b32_e64 v108, 0, 1, s[86:87]
	v_cndmask_b32_e64 v109, 0, 1, s[88:89]
	v_sub_f32_e32 v106, v206, v106
	v_cndmask_b32_e64 v108, v109, v108, s[14:15]
	v_mul_f32_e32 v106, 0x3fb8aa3b, v106
	v_and_b32_e32 v108, 1, v108
	v_cndmask_b32_e32 v106, v232, v106, vcc
	v_cmp_eq_u32_e32 vcc, 1, v108
	v_cndmask_b32_e64 v108, 0, 1, s[90:91]
	v_cndmask_b32_e64 v109, 0, 1, s[92:93]
	v_sub_f32_e32 v107, v206, v107
	v_cndmask_b32_e64 v108, v109, v108, s[14:15]
	v_mul_f32_e32 v107, 0x3fb8aa3b, v107
	v_and_b32_e32 v108, 1, v108
	v_cndmask_b32_e32 v107, v232, v107, vcc
	v_cmp_eq_u32_e32 vcc, 1, v108
	v_cndmask_b32_e64 v108, 0, 1, s[94:95]
	v_cndmask_b32_e64 v109, 0, 1, s[96:97]
	s_waitcnt lgkmcnt(0)
	v_sub_f32_e32 v100, v206, v100
	v_cndmask_b32_e64 v108, v109, v108, s[14:15]
	v_mul_f32_e32 v100, 0x3fb8aa3b, v100
	v_and_b32_e32 v108, 1, v108
	v_sub_f32_e32 v101, v206, v101
	v_cndmask_b32_e32 v100, v232, v100, vcc
	v_cmp_eq_u32_e32 vcc, 1, v108
	v_mul_f32_e32 v101, 0x3fb8aa3b, v101
	v_exp_f32_e32 v100, v100
	v_cndmask_b32_e32 v101, v232, v101, vcc
	v_exp_f32_e32 v101, v101
	v_exp_f32_e32 v104, v104
	v_exp_f32_e32 v105, v105
	v_exp_f32_e32 v106, v106
	v_pk_mul_f32 v[108:109], v[60:61], v[100:101]
	v_cndmask_b32_e64 v100, 0, 1, s[2:3]
	v_cndmask_b32_e64 v101, 0, 1, s[8:9]
	v_cndmask_b32_e64 v100, v101, v100, s[14:15]
	v_and_b32_e32 v100, 1, v100
	v_cmp_eq_u32_e32 vcc, 1, v100
	v_sub_f32_e32 v100, v206, v102
	v_cndmask_b32_e64 v101, 0, 1, s[0:1]
	v_cndmask_b32_e64 v102, 0, 1, s[10:11]
	v_cndmask_b32_e64 v101, v102, v101, s[14:15]
	v_mul_f32_e32 v100, 0x3fb8aa3b, v100
	v_and_b32_e32 v101, 1, v101
	v_cndmask_b32_e32 v100, v232, v100, vcc
	v_cmp_eq_u32_e32 vcc, 1, v101
	v_sub_f32_e32 v101, v206, v103
	v_mul_f32_e32 v101, 0x3fb8aa3b, v101
	v_cndmask_b32_e32 v101, v232, v101, vcc
	v_exp_f32_e32 v107, v107
	v_exp_f32_e32 v100, v100
	v_exp_f32_e32 v101, v101
	v_pk_mul_f32 v[104:105], v[56:57], v[104:105]
	v_pk_mul_f32 v[106:107], v[58:59], v[106:107]
	v_cvt_pk_bf16_f32 v102, v108, v109
	v_pk_mul_f32 v[112:113], v[62:63], v[100:101]
	v_cvt_pk_bf16_f32 v100, v104, v105
	v_cvt_pk_bf16_f32 v101, v106, v107
	v_cvt_pk_bf16_f32 v103, v112, v113
	s_nop 1
	v_mfma_f32_32x32x16_bf16 v[80:95], v[100:103], v[96:99], v[80:95]
	ds_read2_b64 v[96:99], v110 offset0:92 offset1:94
	s_waitcnt lgkmcnt(0)
	v_mfma_f32_32x32x16_bf16 v[64:79], v[100:103], v[96:99], v[64:79]
	s_branch .LBB0_2104

	.amdhsa_kernel _Z4mega6Params
		.amdhsa_group_segment_fixed_size 131088
		.amdhsa_private_segment_fixed_size 0
		.amdhsa_kernarg_size 496
		.amdhsa_user_sgpr_count 2
		.amdhsa_user_sgpr_dispatch_ptr 0
		.amdhsa_user_sgpr_queue_ptr 0
		.amdhsa_user_sgpr_kernarg_segment_ptr 1
		.amdhsa_user_sgpr_dispatch_id 0
		.amdhsa_user_sgpr_kernarg_preload_length 0
		.amdhsa_user_sgpr_kernarg_preload_offset 0
		.amdhsa_user_sgpr_private_segment_size 0
		.amdhsa_uses_dynamic_stack 0
		.amdhsa_enable_private_segment 0
		.amdhsa_system_sgpr_workgroup_id_x 1
		.amdhsa_system_sgpr_workgroup_id_y 0
		.amdhsa_system_sgpr_workgroup_id_z 0
		.amdhsa_system_sgpr_workgroup_info 0
		.amdhsa_system_vgpr_workitem_id 2
		.amdhsa_next_free_vgpr 256
		.amdhsa_next_free_sgpr 102
		.amdhsa_accum_offset 256
		.amdhsa_reserve_vcc 1
		.amdhsa_float_round_mode_32 0
		.amdhsa_float_round_mode_16_64 0
		.amdhsa_float_denorm_mode_32 3
		.amdhsa_float_denorm_mode_16_64 3
		.amdhsa_dx10_clamp 1
		.amdhsa_ieee_mode 1
		.amdhsa_fp16_overflow 0
		.amdhsa_tg_split 0
		.amdhsa_exception_fp_ieee_invalid_op 0
		.amdhsa_exception_fp_denorm_src 0
		.amdhsa_exception_fp_ieee_div_zero 0
		.amdhsa_exception_fp_ieee_overflow 0
		.amdhsa_exception_fp_ieee_underflow 0
		.amdhsa_exception_fp_ieee_inexact 0
		.amdhsa_exception_int_div_zero 0
	.end_amdhsa_kernel

amdhsa.kernels:
  - .agpr_count:     0
    .args:
      - .offset:         0
        .size:           240
        .value_kind:     by_value
      - .offset:         240
        .size:           4
        .value_kind:     hidden_block_count_x
      - .offset:         244
        .size:           4
        .value_kind:     hidden_block_count_y
      - .offset:         248
        .size:           4
        .value_kind:     hidden_block_count_z
      - .offset:         252
        .size:           2
        .value_kind:     hidden_group_size_x
      - .offset:         254
        .size:           2
        .value_kind:     hidden_group_size_y
      - .offset:         256
        .size:           2
        .value_kind:     hidden_group_size_z
      - .offset:         258
        .size:           2
        .value_kind:     hidden_remainder_x
      - .offset:         260
        .size:           2
        .value_kind:     hidden_remainder_y
      - .offset:         262
        .size:           2
        .value_kind:     hidden_remainder_z
      - .offset:         280
        .size:           8
        .value_kind:     hidden_global_offset_x
      - .offset:         288
        .size:           8
        .value_kind:     hidden_global_offset_y
      - .offset:         296
        .size:           8
        .value_kind:     hidden_global_offset_z
      - .offset:         304
        .size:           2
        .value_kind:     hidden_grid_dims
      - .offset:         328
        .size:           8
        .value_kind:     hidden_multigrid_sync_arg
    .group_segment_fixed_size: 131088
    .kernarg_segment_align: 8
    .kernarg_segment_size: 496
    .language:       OpenCL C
    .language_version:
      - 2
      - 0
    .max_flat_workgroup_size: 512
    .name:           _Z4mega6Params
    .private_segment_fixed_size: 0
    .sgpr_count:     108
    .sgpr_spill_count: 332
    .symbol:         _Z4mega6Params.kd
    .uniform_work_group_size: 1
    .uses_dynamic_stack: false
    .vgpr_count:     256
    .vgpr_spill_count: 0
    .wavefront_size: 64
